# MFMA order in all K-loops: accumulate chains (k0,k1) adjacent, chains grouped by B fragment (dependency-aware reorder inside each MFMA block)
# speedup vs baseline: 1.0530x; 1.0132x over previous
.LBB0_120:
	s_and_b64 vcc, exec, s[6:7]
	s_cbranch_vccz .LBB0_122
	s_waitcnt lgkmcnt(0)
	ds_read_b128 v[4:7], v151
	ds_read_b128 v[8:11], v151 offset:1024
	ds_read_b128 v[12:15], v151 offset:2048
	ds_read_b128 v[16:19], v151 offset:3072
	ds_read_b128 v[20:23], v152
	ds_read_b128 v[24:27], v152 offset:1024
	ds_read_b128 v[28:31], v152 offset:2048
	ds_read_b128 v[32:35], v152 offset:3072
	s_or_b32 s9, s11, 0x100
	s_or_b32 s3, s11, 0x80180
	s_or_b32 s6, s10, 0x80100
	s_or_b32 s7, s11, 0x80100
	s_or_b32 s8, s11, 0x180
	s_or_b32 s12, s10, 0x100
	ds_read_b128 v[36:39], v153
	ds_read_b128 v[40:43], v153 offset:1024
	ds_read_b128 v[44:47], v153 offset:2048
	ds_read_b128 v[48:51], v153 offset:3072
	ds_read_b128 v[52:55], v153 offset:4096
	ds_read_b128 v[56:59], v153 offset:5120
	ds_read_b128 v[60:63], v153 offset:6144
	ds_read_b128 v[64:67], v153 offset:7168
	s_waitcnt vmcnt(24)
	s_waitcnt lgkmcnt(0)
	s_barrier
	s_setprio 1
	s_waitcnt lgkmcnt(1)
	v_mfma_f32_16x16x32_bf16 v[92:95], v[4:7], v[60:63], 0
	v_mfma_f32_16x16x32_bf16 v[68:71], v[4:7], v[36:39], 0
	v_mfma_f32_16x16x32_bf16 v[72:75], v[12:15], v[36:39], 0
	v_mfma_f32_16x16x32_bf16 v[76:79], v[4:7], v[44:47], 0
	v_mfma_f32_16x16x32_bf16 v[80:83], v[12:15], v[44:47], 0
	v_mfma_f32_16x16x32_bf16 v[84:87], v[4:7], v[52:55], 0
	v_mfma_f32_16x16x32_bf16 v[88:91], v[12:15], v[52:55], 0
	s_waitcnt lgkmcnt(0)
	v_mfma_f32_16x16x32_bf16 v[102:105], v[8:11], v[64:67], v[92:95]
	v_mfma_f32_16x16x32_bf16 v[92:95], v[12:15], v[60:63], 0
	v_mfma_f32_16x16x32_bf16 v[68:71], v[8:11], v[40:43], v[68:71]
	v_mfma_f32_16x16x32_bf16 v[76:79], v[8:11], v[48:51], v[76:79]
	v_mfma_f32_16x16x32_bf16 v[84:87], v[8:11], v[56:59], v[84:87]
	v_mfma_f32_16x16x32_bf16 v[72:75], v[16:19], v[40:43], v[72:75]
	v_mfma_f32_16x16x32_bf16 v[80:83], v[16:19], v[48:51], v[80:83]
	v_mfma_f32_16x16x32_bf16 v[88:91], v[16:19], v[56:59], v[88:91]
	v_mfma_f32_16x16x32_bf16 v[106:109], v[16:19], v[64:67], v[92:95]
	s_setprio 0
	s_setprio 1
	v_mfma_f32_16x16x32_bf16 v[92:95], v[20:23], v[36:39], 0
	v_mfma_f32_16x16x32_bf16 v[36:39], v[28:31], v[36:39], 0
	v_mfma_f32_16x16x32_bf16 v[118:121], v[24:27], v[40:43], v[92:95]
	v_mfma_f32_16x16x32_bf16 v[36:39], v[32:35], v[40:43], v[36:39]
	v_mfma_f32_16x16x32_bf16 v[40:43], v[20:23], v[44:47], 0
	v_mfma_f32_16x16x32_bf16 v[44:47], v[28:31], v[44:47], 0
	v_mfma_f32_16x16x32_bf16 v[40:43], v[24:27], v[48:51], v[40:43]
	v_mfma_f32_16x16x32_bf16 v[44:47], v[32:35], v[48:51], v[44:47]
	v_mfma_f32_16x16x32_bf16 v[48:51], v[20:23], v[52:55], 0
	v_mfma_f32_16x16x32_bf16 v[52:55], v[28:31], v[52:55], 0
	v_mfma_f32_16x16x32_bf16 v[48:51], v[24:27], v[56:59], v[48:51]
	v_mfma_f32_16x16x32_bf16 v[52:55], v[32:35], v[56:59], v[52:55]
	v_mfma_f32_16x16x32_bf16 v[56:59], v[20:23], v[60:63], 0
	v_mfma_f32_16x16x32_bf16 v[60:63], v[28:31], v[60:63], 0
	v_mfma_f32_16x16x32_bf16 v[56:59], v[24:27], v[64:67], v[56:59]
	v_mfma_f32_16x16x32_bf16 v[60:63], v[32:35], v[64:67], v[60:63]
	s_setprio 0
	s_barrier
	s_mov_b32 m0, s91
	s_mov_b32 s75, s31
	ds_read_b128 v[64:67], v153 offset:16384
	ds_read_b128 v[92:95], v153 offset:17408
	buffer_load_dwordx4 v146, s[72:75], s9 offen lds
	s_mov_b32 m0, s93
	ds_read_b128 v[96:99], v153 offset:18432
	ds_read_b128 v[110:113], v153 offset:19456
	buffer_load_dwordx4 v148, s[72:75], s9 offen lds
	s_mov_b32 m0, s95
	ds_read_b128 v[114:117], v153 offset:20480
	ds_read_b128 v[122:125], v153 offset:21504
	buffer_load_dwordx4 v146, s[72:75], s7 offen lds
	s_mov_b32 m0, s35
	ds_read_b128 v[126:129], v153 offset:22528
	ds_read_b128 v[130:133], v153 offset:23552
	buffer_load_dwordx4 v148, s[72:75], s7 offen lds
	s_waitcnt vmcnt(22)
	s_waitcnt lgkmcnt(0)
	s_barrier
	s_setprio 1
	s_waitcnt lgkmcnt(7)
	v_mfma_f32_16x16x32_bf16 v[138:141], v[4:7], v[64:67], 0
	s_waitcnt lgkmcnt(5)
	v_mfma_f32_16x16x32_bf16 v[158:161], v[4:7], v[96:99], 0
	s_waitcnt lgkmcnt(3)
	v_mfma_f32_16x16x32_bf16 v[166:169], v[4:7], v[114:117], 0
	s_waitcnt lgkmcnt(1)
	v_mfma_f32_16x16x32_bf16 v[4:7], v[4:7], v[126:129], 0
	s_waitcnt lgkmcnt(0)
	v_mfma_f32_16x16x32_bf16 v[138:141], v[8:11], v[92:95], v[138:141]
	v_mfma_f32_16x16x32_bf16 v[158:161], v[8:11], v[110:113], v[158:161]
	v_mfma_f32_16x16x32_bf16 v[166:169], v[8:11], v[122:125], v[166:169]
	v_mfma_f32_16x16x32_bf16 v[4:7], v[8:11], v[130:133], v[4:7]
	v_mfma_f32_16x16x32_bf16 v[8:11], v[12:15], v[126:129], 0
	v_mfma_f32_16x16x32_bf16 v[142:145], v[12:15], v[64:67], 0
	v_mfma_f32_16x16x32_bf16 v[162:165], v[12:15], v[96:99], 0
	v_mfma_f32_16x16x32_bf16 v[170:173], v[12:15], v[114:117], 0
	v_mfma_f32_16x16x32_bf16 v[8:11], v[16:19], v[130:133], v[8:11]
	v_mfma_f32_16x16x32_bf16 v[142:145], v[16:19], v[92:95], v[142:145]
	v_mfma_f32_16x16x32_bf16 v[162:165], v[16:19], v[110:113], v[162:165]
	v_mfma_f32_16x16x32_bf16 v[170:173], v[16:19], v[122:125], v[170:173]
	s_setprio 0
	s_setprio 1
	v_mfma_f32_16x16x32_bf16 v[12:15], v[20:23], v[64:67], 0
	v_mfma_f32_16x16x32_bf16 v[174:177], v[24:27], v[92:95], v[12:15]
	v_mfma_f32_16x16x32_bf16 v[12:15], v[28:31], v[64:67], 0
	v_mfma_f32_16x16x32_bf16 v[178:181], v[32:35], v[92:95], v[12:15]
	v_mfma_f32_16x16x32_bf16 v[12:15], v[20:23], v[96:99], 0
	v_mfma_f32_16x16x32_bf16 v[182:185], v[24:27], v[110:113], v[12:15]
	v_mfma_f32_16x16x32_bf16 v[12:15], v[28:31], v[96:99], 0
	v_mfma_f32_16x16x32_bf16 v[186:189], v[32:35], v[110:113], v[12:15]
	v_mfma_f32_16x16x32_bf16 v[12:15], v[20:23], v[114:117], 0
	v_mfma_f32_16x16x32_bf16 v[190:193], v[24:27], v[122:125], v[12:15]
	v_mfma_f32_16x16x32_bf16 v[12:15], v[28:31], v[114:117], 0
	v_mfma_f32_16x16x32_bf16 v[194:197], v[32:35], v[122:125], v[12:15]
	v_mfma_f32_16x16x32_bf16 v[12:15], v[20:23], v[126:129], 0
	v_mfma_f32_16x16x32_bf16 v[198:201], v[24:27], v[130:133], v[12:15]
	v_mfma_f32_16x16x32_bf16 v[12:15], v[28:31], v[126:129], 0
	v_mfma_f32_16x16x32_bf16 v[202:205], v[32:35], v[130:133], v[12:15]
	s_setprio 0
	s_barrier
	s_nop 4
	ds_read_b128 v[12:15], v154
	ds_read_b128 v[16:19], v154 offset:1024
	ds_read_b128 v[22:25], v154 offset:2048
	ds_read_b128 v[26:29], v154 offset:3072
	ds_read_b128 v[206:209], v155
	ds_read_b128 v[210:213], v155 offset:1024
	ds_read_b128 v[214:217], v155 offset:2048
	ds_read_b128 v[218:221], v155 offset:3072
	s_mov_b32 m0, s77
	ds_read_b128 v[30:33], v153 offset:32768
	ds_read_b128 v[64:67], v153 offset:33792
	buffer_load_dwordx4 v1, s[28:31], s12 offen lds
	s_mov_b32 m0, s84
	ds_read_b128 v[222:225], v153 offset:34816
	ds_read_b128 v[226:229], v153 offset:35840
	buffer_load_dwordx4 v147, s[28:31], s12 offen lds
	s_mov_b32 m0, s85
	ds_read_b128 v[230:233], v153 offset:36864
	ds_read_b128 v[236:239], v153 offset:37888
	buffer_load_dwordx4 v1, s[28:31], s6 offen lds
	s_mov_b32 m0, s48
	ds_read_b128 v[240:243], v153 offset:38912
	ds_read_b128 v[244:247], v153 offset:39936
	buffer_load_dwordx4 v147, s[28:31], s6 offen lds
	s_waitcnt vmcnt(24)
	s_waitcnt lgkmcnt(0)
	s_barrier
	s_setprio 1
	s_waitcnt lgkmcnt(0)
	v_mfma_f32_16x16x32_bf16 v[68:71], v[12:15], v[30:33], v[68:71]
	v_mfma_f32_16x16x32_bf16 v[130:133], v[16:19], v[64:67], v[68:71]
	v_mfma_f32_16x16x32_bf16 v[68:71], v[22:25], v[30:33], v[72:75]
	v_mfma_f32_16x16x32_bf16 v[126:129], v[26:29], v[64:67], v[68:71]
	v_mfma_f32_16x16x32_bf16 v[68:71], v[12:15], v[222:225], v[76:79]
	v_mfma_f32_16x16x32_bf16 v[114:117], v[16:19], v[226:229], v[68:71]
	v_mfma_f32_16x16x32_bf16 v[68:71], v[22:25], v[222:225], v[80:83]
	v_mfma_f32_16x16x32_bf16 v[110:113], v[26:29], v[226:229], v[68:71]
	v_mfma_f32_16x16x32_bf16 v[68:71], v[12:15], v[230:233], v[84:87]
	v_mfma_f32_16x16x32_bf16 v[98:101], v[16:19], v[236:239], v[68:71]
	v_mfma_f32_16x16x32_bf16 v[68:71], v[22:25], v[230:233], v[88:91]
	v_mfma_f32_16x16x32_bf16 v[94:97], v[26:29], v[236:239], v[68:71]
	v_mfma_f32_16x16x32_bf16 v[68:71], v[12:15], v[240:243], v[102:105]
	v_mfma_f32_16x16x32_bf16 v[82:85], v[16:19], v[244:247], v[68:71]
	v_mfma_f32_16x16x32_bf16 v[68:71], v[22:25], v[240:243], v[106:109]
	v_mfma_f32_16x16x32_bf16 v[78:81], v[26:29], v[244:247], v[68:71]
	s_setprio 0
	s_setprio 1
	v_mfma_f32_16x16x32_bf16 v[68:71], v[206:209], v[30:33], v[118:121]
	v_mfma_f32_16x16x32_bf16 v[122:125], v[210:213], v[64:67], v[68:71]
	v_mfma_f32_16x16x32_bf16 v[30:33], v[214:217], v[30:33], v[36:39]
	v_mfma_f32_16x16x32_bf16 v[118:121], v[218:221], v[64:67], v[30:33]
	v_mfma_f32_16x16x32_bf16 v[30:33], v[206:209], v[222:225], v[40:43]
	v_mfma_f32_16x16x32_bf16 v[106:109], v[210:213], v[226:229], v[30:33]
	v_mfma_f32_16x16x32_bf16 v[30:33], v[214:217], v[222:225], v[44:47]
	v_mfma_f32_16x16x32_bf16 v[102:105], v[218:221], v[226:229], v[30:33]
	v_mfma_f32_16x16x32_bf16 v[30:33], v[206:209], v[230:233], v[48:51]
	v_mfma_f32_16x16x32_bf16 v[90:93], v[210:213], v[236:239], v[30:33]
	v_mfma_f32_16x16x32_bf16 v[30:33], v[214:217], v[230:233], v[52:55]
	v_mfma_f32_16x16x32_bf16 v[86:89], v[218:221], v[236:239], v[30:33]
	v_mfma_f32_16x16x32_bf16 v[30:33], v[206:209], v[240:243], v[56:59]
	v_mfma_f32_16x16x32_bf16 v[74:77], v[210:213], v[244:247], v[30:33]
	v_mfma_f32_16x16x32_bf16 v[30:33], v[214:217], v[240:243], v[60:63]
	v_mfma_f32_16x16x32_bf16 v[70:73], v[218:221], v[244:247], v[30:33]
	s_setprio 0
	s_barrier
	s_mov_b32 m0, s78
	ds_read_b128 v[38:41], v153 offset:49152
	ds_read_b128 v[42:45], v153 offset:50176
	buffer_load_dwordx4 v146, s[72:75], s8 offen lds
	s_mov_b32 m0, s79
	ds_read_b128 v[222:225], v153 offset:51200
	ds_read_b128 v[226:229], v153 offset:52224
	buffer_load_dwordx4 v148, s[72:75], s8 offen lds
	s_mov_b32 m0, s86
	ds_read_b128 v[230:233], v153 offset:53248
	ds_read_b128 v[236:239], v153 offset:54272
	buffer_load_dwordx4 v146, s[72:75], s3 offen lds
	s_mov_b32 m0, s87
	ds_read_b128 v[240:243], v153 offset:55296
	ds_read_b128 v[244:247], v153 offset:56320
	buffer_load_dwordx4 v148, s[72:75], s3 offen lds
	s_waitcnt vmcnt(6)
	s_waitcnt lgkmcnt(0)
	s_barrier
	s_setprio 1
	s_waitcnt lgkmcnt(0)
	v_mfma_f32_16x16x32_bf16 v[30:33], v[12:15], v[38:41], v[138:141]
	v_mfma_f32_16x16x32_bf16 v[66:69], v[16:19], v[42:45], v[30:33]
	v_mfma_f32_16x16x32_bf16 v[4:7], v[12:15], v[240:243], v[4:7]
	v_mfma_f32_16x16x32_bf16 v[30:33], v[22:25], v[38:41], v[142:145]
	v_mfma_f32_16x16x32_bf16 v[62:65], v[26:29], v[42:45], v[30:33]
	v_mfma_f32_16x16x32_bf16 v[30:33], v[12:15], v[222:225], v[158:161]
	v_mfma_f32_16x16x32_bf16 v[50:53], v[16:19], v[226:229], v[30:33]
	v_mfma_f32_16x16x32_bf16 v[30:33], v[22:25], v[222:225], v[162:165]
	v_mfma_f32_16x16x32_bf16 v[46:49], v[26:29], v[226:229], v[30:33]
	v_mfma_f32_16x16x32_bf16 v[30:33], v[12:15], v[230:233], v[166:169]
	v_mfma_f32_16x16x32_bf16 v[34:37], v[16:19], v[236:239], v[30:33]
	v_mfma_f32_16x16x32_bf16 v[18:21], v[16:19], v[244:247], v[4:7]
	v_mfma_f32_16x16x32_bf16 v[30:33], v[22:25], v[230:233], v[170:173]
	v_mfma_f32_16x16x32_bf16 v[30:33], v[26:29], v[236:239], v[30:33]
	v_mfma_f32_16x16x32_bf16 v[4:7], v[22:25], v[240:243], v[8:11]
	v_mfma_f32_16x16x32_bf16 v[14:17], v[26:29], v[244:247], v[4:7]
	s_setprio 0
	s_setprio 1
	v_mfma_f32_16x16x32_bf16 v[4:7], v[206:209], v[38:41], v[174:177]
	v_mfma_f32_16x16x32_bf16 v[58:61], v[210:213], v[42:45], v[4:7]
	v_mfma_f32_16x16x32_bf16 v[4:7], v[214:217], v[38:41], v[178:181]
	v_mfma_f32_16x16x32_bf16 v[54:57], v[218:221], v[42:45], v[4:7]
	v_mfma_f32_16x16x32_bf16 v[4:7], v[206:209], v[222:225], v[182:185]
	v_mfma_f32_16x16x32_bf16 v[42:45], v[210:213], v[226:229], v[4:7]
	v_mfma_f32_16x16x32_bf16 v[4:7], v[214:217], v[222:225], v[186:189]
	v_mfma_f32_16x16x32_bf16 v[38:41], v[218:221], v[226:229], v[4:7]
	v_mfma_f32_16x16x32_bf16 v[4:7], v[206:209], v[230:233], v[190:193]
	v_mfma_f32_16x16x32_bf16 v[26:29], v[210:213], v[236:239], v[4:7]
	v_mfma_f32_16x16x32_bf16 v[4:7], v[214:217], v[230:233], v[194:197]
	v_mfma_f32_16x16x32_bf16 v[22:25], v[218:221], v[236:239], v[4:7]
	v_mfma_f32_16x16x32_bf16 v[4:7], v[206:209], v[240:243], v[198:201]
	v_mfma_f32_16x16x32_bf16 v[10:13], v[210:213], v[244:247], v[4:7]
	v_mfma_f32_16x16x32_bf16 v[4:7], v[214:217], v[240:243], v[202:205]
	v_mfma_f32_16x16x32_bf16 v[6:9], v[218:221], v[244:247], v[4:7]
	s_setprio 0
	s_barrier
	s_mov_b32 s9, 2
	s_branch .LBB0_123

.LBB0_124:
	ds_read_b128 v[138:141], v151
	ds_read_b128 v[142:145], v151 offset:1024
	ds_read_b128 v[158:161], v151 offset:2048
	ds_read_b128 v[162:165], v151 offset:3072
	ds_read_b128 v[166:169], v152
	ds_read_b128 v[170:173], v152 offset:1024
	ds_read_b128 v[174:177], v152 offset:2048
	ds_read_b128 v[178:181], v152 offset:3072
	s_add_i32 s47, s9, s10
	s_add_i32 s75, s47, 0x100
	s_add_i32 s13, s9, s11
	s_cmp_eq_u32 s9, s12
	s_cselect_b32 s13, s7, s13
	s_cselect_b32 s80, s6, s75
	s_add_i32 s75, s47, 0x80
	s_mov_b32 m0, s58
	ds_read_b128 v[182:185], v153
	ds_read_b128 v[186:189], v153 offset:1024
	buffer_load_dwordx4 v1, s[28:31], s75 offen lds
	s_mov_b32 m0, s59
	ds_read_b128 v[190:193], v153 offset:2048
	ds_read_b128 v[194:197], v153 offset:3072
	buffer_load_dwordx4 v147, s[28:31], s75 offen lds
	s_add_i32 s47, s47, 0x80080
	s_mov_b32 m0, s70
	ds_read_b128 v[198:201], v153 offset:4096
	ds_read_b128 v[202:205], v153 offset:5120
	buffer_load_dwordx4 v1, s[28:31], s47 offen lds
	s_mov_b32 m0, s71
	ds_read_b128 v[206:209], v153 offset:6144
	ds_read_b128 v[210:213], v153 offset:7168
	buffer_load_dwordx4 v147, s[28:31], s47 offen lds
	s_waitcnt vmcnt(8)
	s_waitcnt lgkmcnt(0)
	s_barrier
	s_setprio 1
	s_waitcnt lgkmcnt(0)
	v_mfma_f32_16x16x32_bf16 v[130:133], v[138:141], v[182:185], v[130:133]
	v_mfma_f32_16x16x32_bf16 v[130:133], v[142:145], v[186:189], v[130:133]
	v_mfma_f32_16x16x32_bf16 v[114:117], v[138:141], v[190:193], v[114:117]
	v_mfma_f32_16x16x32_bf16 v[114:117], v[142:145], v[194:197], v[114:117]
	v_mfma_f32_16x16x32_bf16 v[98:101], v[138:141], v[198:201], v[98:101]
	v_mfma_f32_16x16x32_bf16 v[98:101], v[142:145], v[202:205], v[98:101]
	v_mfma_f32_16x16x32_bf16 v[82:85], v[138:141], v[206:209], v[82:85]
	v_mfma_f32_16x16x32_bf16 v[82:85], v[142:145], v[210:213], v[82:85]
	v_mfma_f32_16x16x32_bf16 v[126:129], v[158:161], v[182:185], v[126:129]
	v_mfma_f32_16x16x32_bf16 v[126:129], v[162:165], v[186:189], v[126:129]
	v_mfma_f32_16x16x32_bf16 v[110:113], v[158:161], v[190:193], v[110:113]
	v_mfma_f32_16x16x32_bf16 v[110:113], v[162:165], v[194:197], v[110:113]
	v_mfma_f32_16x16x32_bf16 v[94:97], v[158:161], v[198:201], v[94:97]
	v_mfma_f32_16x16x32_bf16 v[94:97], v[162:165], v[202:205], v[94:97]
	v_mfma_f32_16x16x32_bf16 v[78:81], v[158:161], v[206:209], v[78:81]
	v_mfma_f32_16x16x32_bf16 v[78:81], v[162:165], v[210:213], v[78:81]
	s_setprio 0
	s_setprio 1
	v_mfma_f32_16x16x32_bf16 v[122:125], v[166:169], v[182:185], v[122:125]
	v_mfma_f32_16x16x32_bf16 v[122:125], v[170:173], v[186:189], v[122:125]
	v_mfma_f32_16x16x32_bf16 v[106:109], v[166:169], v[190:193], v[106:109]
	v_mfma_f32_16x16x32_bf16 v[106:109], v[170:173], v[194:197], v[106:109]
	v_mfma_f32_16x16x32_bf16 v[90:93], v[166:169], v[198:201], v[90:93]
	v_mfma_f32_16x16x32_bf16 v[90:93], v[170:173], v[202:205], v[90:93]
	v_mfma_f32_16x16x32_bf16 v[74:77], v[166:169], v[206:209], v[74:77]
	v_mfma_f32_16x16x32_bf16 v[74:77], v[170:173], v[210:213], v[74:77]
	v_mfma_f32_16x16x32_bf16 v[118:121], v[174:177], v[182:185], v[118:121]
	v_mfma_f32_16x16x32_bf16 v[118:121], v[178:181], v[186:189], v[118:121]
	v_mfma_f32_16x16x32_bf16 v[102:105], v[174:177], v[190:193], v[102:105]
	v_mfma_f32_16x16x32_bf16 v[102:105], v[178:181], v[194:197], v[102:105]
	v_mfma_f32_16x16x32_bf16 v[86:89], v[174:177], v[198:201], v[86:89]
	v_mfma_f32_16x16x32_bf16 v[86:89], v[178:181], v[202:205], v[86:89]
	v_mfma_f32_16x16x32_bf16 v[70:73], v[174:177], v[206:209], v[70:73]
	v_mfma_f32_16x16x32_bf16 v[70:73], v[178:181], v[210:213], v[70:73]
	s_setprio 0
	s_barrier
	s_mov_b32 m0, s91
	s_mov_b32 s75, s31
	ds_read_b128 v[182:185], v153 offset:16384
	ds_read_b128 v[186:189], v153 offset:17408
	buffer_load_dwordx4 v146, s[72:75], s13 offen lds
	s_mov_b32 m0, s93
	ds_read_b128 v[190:193], v153 offset:18432
	ds_read_b128 v[194:197], v153 offset:19456
	buffer_load_dwordx4 v148, s[72:75], s13 offen lds
	s_add_i32 s47, s13, 0x80000
	s_mov_b32 m0, s95
	ds_read_b128 v[198:201], v153 offset:20480
	ds_read_b128 v[202:205], v153 offset:21504
	buffer_load_dwordx4 v146, s[72:75], s47 offen lds
	s_mov_b32 m0, s35
	ds_read_b128 v[206:209], v153 offset:22528
	ds_read_b128 v[210:213], v153 offset:23552
	buffer_load_dwordx4 v148, s[72:75], s47 offen lds
	s_waitcnt vmcnt(6)
	s_waitcnt lgkmcnt(0)
	s_barrier
	s_setprio 1
	s_waitcnt lgkmcnt(0)
	v_mfma_f32_16x16x32_bf16 v[66:69], v[138:141], v[182:185], v[66:69]
	v_mfma_f32_16x16x32_bf16 v[66:69], v[142:145], v[186:189], v[66:69]
	v_mfma_f32_16x16x32_bf16 v[50:53], v[138:141], v[190:193], v[50:53]
	v_mfma_f32_16x16x32_bf16 v[50:53], v[142:145], v[194:197], v[50:53]
	v_mfma_f32_16x16x32_bf16 v[34:37], v[138:141], v[198:201], v[34:37]
	v_mfma_f32_16x16x32_bf16 v[34:37], v[142:145], v[202:205], v[34:37]
	v_mfma_f32_16x16x32_bf16 v[18:21], v[138:141], v[206:209], v[18:21]
	v_mfma_f32_16x16x32_bf16 v[18:21], v[142:145], v[210:213], v[18:21]
	v_mfma_f32_16x16x32_bf16 v[62:65], v[158:161], v[182:185], v[62:65]
	v_mfma_f32_16x16x32_bf16 v[62:65], v[162:165], v[186:189], v[62:65]
	v_mfma_f32_16x16x32_bf16 v[46:49], v[158:161], v[190:193], v[46:49]
	v_mfma_f32_16x16x32_bf16 v[46:49], v[162:165], v[194:197], v[46:49]
	v_mfma_f32_16x16x32_bf16 v[30:33], v[158:161], v[198:201], v[30:33]
	v_mfma_f32_16x16x32_bf16 v[30:33], v[162:165], v[202:205], v[30:33]
	v_mfma_f32_16x16x32_bf16 v[14:17], v[158:161], v[206:209], v[14:17]
	v_mfma_f32_16x16x32_bf16 v[14:17], v[162:165], v[210:213], v[14:17]
	s_setprio 0
	s_setprio 1
	v_mfma_f32_16x16x32_bf16 v[58:61], v[166:169], v[182:185], v[58:61]
	v_mfma_f32_16x16x32_bf16 v[58:61], v[170:173], v[186:189], v[58:61]
	v_mfma_f32_16x16x32_bf16 v[42:45], v[166:169], v[190:193], v[42:45]
	v_mfma_f32_16x16x32_bf16 v[42:45], v[170:173], v[194:197], v[42:45]
	v_mfma_f32_16x16x32_bf16 v[26:29], v[166:169], v[198:201], v[26:29]
	v_mfma_f32_16x16x32_bf16 v[26:29], v[170:173], v[202:205], v[26:29]
	v_mfma_f32_16x16x32_bf16 v[10:13], v[166:169], v[206:209], v[10:13]
	v_mfma_f32_16x16x32_bf16 v[10:13], v[170:173], v[210:213], v[10:13]
	v_mfma_f32_16x16x32_bf16 v[54:57], v[174:177], v[182:185], v[54:57]
	v_mfma_f32_16x16x32_bf16 v[54:57], v[178:181], v[186:189], v[54:57]
	v_mfma_f32_16x16x32_bf16 v[38:41], v[174:177], v[190:193], v[38:41]
	v_mfma_f32_16x16x32_bf16 v[38:41], v[178:181], v[194:197], v[38:41]
	v_mfma_f32_16x16x32_bf16 v[22:25], v[174:177], v[198:201], v[22:25]
	v_mfma_f32_16x16x32_bf16 v[22:25], v[178:181], v[202:205], v[22:25]
	v_mfma_f32_16x16x32_bf16 v[4:7], v[174:177], v[206:209], v[6:9]
	v_mfma_f32_16x16x32_bf16 v[4:7], v[178:181], v[210:213], v[4:7]
	s_setprio 0
	s_barrier
	ds_read_b128 v[138:141], v154
	ds_read_b128 v[142:145], v154 offset:1024
	ds_read_b128 v[158:161], v154 offset:2048
	ds_read_b128 v[162:165], v154 offset:3072
	ds_read_b128 v[166:169], v155
	ds_read_b128 v[170:173], v155 offset:1024
	ds_read_b128 v[174:177], v155 offset:2048
	ds_read_b128 v[178:181], v155 offset:3072
	s_mov_b32 m0, s77
	ds_read_b128 v[182:185], v153 offset:32768
	ds_read_b128 v[186:189], v153 offset:33792
	buffer_load_dwordx4 v1, s[28:31], s80 offen lds
	s_mov_b32 m0, s84
	ds_read_b128 v[190:193], v153 offset:34816
	ds_read_b128 v[194:197], v153 offset:35840
	buffer_load_dwordx4 v147, s[28:31], s80 offen lds
	s_add_i32 s80, s80, 0x80000
	s_mov_b32 m0, s85
	ds_read_b128 v[198:201], v153 offset:36864
	ds_read_b128 v[202:205], v153 offset:37888
	buffer_load_dwordx4 v1, s[28:31], s80 offen lds
	s_mov_b32 m0, s48
	ds_read_b128 v[206:209], v153 offset:38912
	ds_read_b128 v[210:213], v153 offset:39936
	buffer_load_dwordx4 v147, s[28:31], s80 offen lds
	s_waitcnt vmcnt(8)
	s_waitcnt lgkmcnt(0)
	s_barrier
	s_setprio 1
	s_waitcnt lgkmcnt(0)
	v_mfma_f32_16x16x32_bf16 v[130:133], v[138:141], v[182:185], v[130:133]
	v_mfma_f32_16x16x32_bf16 v[130:133], v[142:145], v[186:189], v[130:133]
	v_mfma_f32_16x16x32_bf16 v[114:117], v[138:141], v[190:193], v[114:117]
	v_mfma_f32_16x16x32_bf16 v[114:117], v[142:145], v[194:197], v[114:117]
	v_mfma_f32_16x16x32_bf16 v[98:101], v[138:141], v[198:201], v[98:101]
	v_mfma_f32_16x16x32_bf16 v[98:101], v[142:145], v[202:205], v[98:101]
	v_mfma_f32_16x16x32_bf16 v[82:85], v[138:141], v[206:209], v[82:85]
	v_mfma_f32_16x16x32_bf16 v[82:85], v[142:145], v[210:213], v[82:85]
	v_mfma_f32_16x16x32_bf16 v[126:129], v[158:161], v[182:185], v[126:129]
	v_mfma_f32_16x16x32_bf16 v[126:129], v[162:165], v[186:189], v[126:129]
	v_mfma_f32_16x16x32_bf16 v[110:113], v[158:161], v[190:193], v[110:113]
	v_mfma_f32_16x16x32_bf16 v[110:113], v[162:165], v[194:197], v[110:113]
	v_mfma_f32_16x16x32_bf16 v[94:97], v[158:161], v[198:201], v[94:97]
	v_mfma_f32_16x16x32_bf16 v[94:97], v[162:165], v[202:205], v[94:97]
	v_mfma_f32_16x16x32_bf16 v[78:81], v[158:161], v[206:209], v[78:81]
	v_mfma_f32_16x16x32_bf16 v[78:81], v[162:165], v[210:213], v[78:81]
	s_setprio 0
	s_setprio 1
	v_mfma_f32_16x16x32_bf16 v[122:125], v[166:169], v[182:185], v[122:125]
	v_mfma_f32_16x16x32_bf16 v[122:125], v[170:173], v[186:189], v[122:125]
	v_mfma_f32_16x16x32_bf16 v[106:109], v[166:169], v[190:193], v[106:109]
	v_mfma_f32_16x16x32_bf16 v[106:109], v[170:173], v[194:197], v[106:109]
	v_mfma_f32_16x16x32_bf16 v[90:93], v[166:169], v[198:201], v[90:93]
	v_mfma_f32_16x16x32_bf16 v[90:93], v[170:173], v[202:205], v[90:93]
	v_mfma_f32_16x16x32_bf16 v[74:77], v[166:169], v[206:209], v[74:77]
	v_mfma_f32_16x16x32_bf16 v[74:77], v[170:173], v[210:213], v[74:77]
	v_mfma_f32_16x16x32_bf16 v[118:121], v[174:177], v[182:185], v[118:121]
	v_mfma_f32_16x16x32_bf16 v[118:121], v[178:181], v[186:189], v[118:121]
	v_mfma_f32_16x16x32_bf16 v[102:105], v[174:177], v[190:193], v[102:105]
	v_mfma_f32_16x16x32_bf16 v[102:105], v[178:181], v[194:197], v[102:105]
	v_mfma_f32_16x16x32_bf16 v[86:89], v[174:177], v[198:201], v[86:89]
	v_mfma_f32_16x16x32_bf16 v[86:89], v[178:181], v[202:205], v[86:89]
	v_mfma_f32_16x16x32_bf16 v[70:73], v[174:177], v[206:209], v[70:73]
	v_mfma_f32_16x16x32_bf16 v[70:73], v[178:181], v[210:213], v[70:73]
	s_setprio 0
	s_barrier
	s_mov_b32 m0, s78
	s_add_i32 s47, s13, 0x80
	ds_read_b128 v[182:185], v153 offset:49152
	ds_read_b128 v[186:189], v153 offset:50176
	buffer_load_dwordx4 v146, s[72:75], s47 offen lds
	s_mov_b32 m0, s79
	ds_read_b128 v[190:193], v153 offset:51200
	ds_read_b128 v[194:197], v153 offset:52224
	buffer_load_dwordx4 v148, s[72:75], s47 offen lds
	s_add_i32 s13, s13, 0x80080
	s_mov_b32 m0, s86
	ds_read_b128 v[198:201], v153 offset:53248
	ds_read_b128 v[202:205], v153 offset:54272
	buffer_load_dwordx4 v146, s[72:75], s13 offen lds
	s_mov_b32 m0, s87
	ds_read_b128 v[206:209], v153 offset:55296
	ds_read_b128 v[210:213], v153 offset:56320
	buffer_load_dwordx4 v148, s[72:75], s13 offen lds
	s_waitcnt vmcnt(6)
	s_waitcnt lgkmcnt(0)
	s_barrier
	s_setprio 1
	s_waitcnt lgkmcnt(0)
	v_mfma_f32_16x16x32_bf16 v[66:69], v[138:141], v[182:185], v[66:69]
	v_mfma_f32_16x16x32_bf16 v[66:69], v[142:145], v[186:189], v[66:69]
	v_mfma_f32_16x16x32_bf16 v[50:53], v[138:141], v[190:193], v[50:53]
	v_mfma_f32_16x16x32_bf16 v[50:53], v[142:145], v[194:197], v[50:53]
	v_mfma_f32_16x16x32_bf16 v[34:37], v[138:141], v[198:201], v[34:37]
	v_mfma_f32_16x16x32_bf16 v[34:37], v[142:145], v[202:205], v[34:37]
	v_mfma_f32_16x16x32_bf16 v[18:21], v[138:141], v[206:209], v[18:21]
	v_mfma_f32_16x16x32_bf16 v[18:21], v[142:145], v[210:213], v[18:21]
	v_mfma_f32_16x16x32_bf16 v[62:65], v[158:161], v[182:185], v[62:65]
	v_mfma_f32_16x16x32_bf16 v[62:65], v[162:165], v[186:189], v[62:65]
	v_mfma_f32_16x16x32_bf16 v[46:49], v[158:161], v[190:193], v[46:49]
	v_mfma_f32_16x16x32_bf16 v[46:49], v[162:165], v[194:197], v[46:49]
	v_mfma_f32_16x16x32_bf16 v[30:33], v[158:161], v[198:201], v[30:33]
	v_mfma_f32_16x16x32_bf16 v[30:33], v[162:165], v[202:205], v[30:33]
	v_mfma_f32_16x16x32_bf16 v[14:17], v[158:161], v[206:209], v[14:17]
	v_mfma_f32_16x16x32_bf16 v[14:17], v[162:165], v[210:213], v[14:17]
	s_setprio 0
	s_setprio 1
	v_mfma_f32_16x16x32_bf16 v[58:61], v[166:169], v[182:185], v[58:61]
	v_mfma_f32_16x16x32_bf16 v[58:61], v[170:173], v[186:189], v[58:61]
	v_mfma_f32_16x16x32_bf16 v[42:45], v[166:169], v[190:193], v[42:45]
	v_mfma_f32_16x16x32_bf16 v[42:45], v[170:173], v[194:197], v[42:45]
	v_mfma_f32_16x16x32_bf16 v[26:29], v[166:169], v[198:201], v[26:29]
	v_mfma_f32_16x16x32_bf16 v[26:29], v[170:173], v[202:205], v[26:29]
	v_mfma_f32_16x16x32_bf16 v[8:11], v[166:169], v[206:209], v[10:13]
	v_mfma_f32_16x16x32_bf16 v[10:13], v[170:173], v[210:213], v[8:11]
	v_mfma_f32_16x16x32_bf16 v[54:57], v[174:177], v[182:185], v[54:57]
	v_mfma_f32_16x16x32_bf16 v[54:57], v[178:181], v[186:189], v[54:57]
	v_mfma_f32_16x16x32_bf16 v[38:41], v[174:177], v[190:193], v[38:41]
	v_mfma_f32_16x16x32_bf16 v[38:41], v[178:181], v[194:197], v[38:41]
	v_mfma_f32_16x16x32_bf16 v[22:25], v[174:177], v[198:201], v[22:25]
	v_mfma_f32_16x16x32_bf16 v[22:25], v[178:181], v[202:205], v[22:25]
	v_mfma_f32_16x16x32_bf16 v[4:7], v[174:177], v[206:209], v[4:7]
	v_mfma_f32_16x16x32_bf16 v[6:9], v[178:181], v[210:213], v[4:7]
	s_setprio 0
	s_barrier
	s_add_i32 s8, s8, 2
	s_addk_i32 s10, 0x100
	s_addk_i32 s11, 0x100
	s_addk_i32 s12, 0xff00
	s_cmp_gt_u32 s8, 29
	s_cbranch_scc0 .LBB0_124
	v_readlane_b32 s6, v254, 26
	v_readlane_b32 s7, v254, 27
	s_and_b64 vcc, exec, s[6:7]
	s_cbranch_vccz .LBB0_127
	s_barrier

.LBB0_528:
	v_add_u32_e32 v3, 0x10000, v171
	ds_read_b128 v[134:137], v3
	ds_read_b128 v[138:141], v3 offset:1024
	ds_read_b128 v[142:145], v3 offset:2048
	ds_read_b128 v[146:149], v3 offset:3072
	v_add_u32_e32 v3, 0x14000, v171
	ds_read_b128 v[150:153], v3
	ds_read_b128 v[154:157], v3 offset:1024
	ds_read_b128 v[174:177], v3 offset:2048
	ds_read_b128 v[178:181], v3 offset:3072
	s_add_i32 s71, s63, s94
	s_add_i32 s97, s71, 0x100
	s_add_i32 s96, s63, s95
	s_cmp_eq_u32 s63, s93
	s_cselect_b32 s96, s90, s96
	s_cselect_b32 s97, s89, s97
	s_add_i32 vcc_lo, s71, 0x80
	s_mov_b32 m0, s79
	ds_read_b128 v[182:185], v172
	ds_read_b128 v[186:189], v172 offset:1024
	buffer_load_dwordx4 v1, s[48:51], vcc_lo offen lds
	s_mov_b32 m0, s80
	ds_read_b128 v[190:193], v172 offset:2048
	ds_read_b128 v[194:197], v172 offset:3072
	buffer_load_dwordx4 v167, s[48:51], vcc_lo offen lds
	s_add_i32 s71, s71, 0xc0080
	s_mov_b32 m0, s81
	ds_read_b128 v[198:201], v172 offset:4096
	ds_read_b128 v[202:205], v172 offset:5120
	buffer_load_dwordx4 v1, s[48:51], s71 offen lds
	s_mov_b32 m0, s82
	ds_read_b128 v[206:209], v172 offset:6144
	ds_read_b128 v[210:213], v172 offset:7168
	buffer_load_dwordx4 v167, s[48:51], s71 offen lds
	s_waitcnt vmcnt(8)
	s_waitcnt lgkmcnt(0)
	s_barrier
	s_setprio 1
	s_waitcnt lgkmcnt(0)
	v_mfma_f32_16x16x32_bf16 v[130:133], v[134:137], v[182:185], v[130:133]
	v_mfma_f32_16x16x32_bf16 v[130:133], v[138:141], v[186:189], v[130:133]
	v_mfma_f32_16x16x32_bf16 v[114:117], v[134:137], v[190:193], v[114:117]
	v_mfma_f32_16x16x32_bf16 v[114:117], v[138:141], v[194:197], v[114:117]
	v_mfma_f32_16x16x32_bf16 v[98:101], v[134:137], v[198:201], v[98:101]
	v_mfma_f32_16x16x32_bf16 v[98:101], v[138:141], v[202:205], v[98:101]
	v_mfma_f32_16x16x32_bf16 v[82:85], v[134:137], v[206:209], v[82:85]
	v_mfma_f32_16x16x32_bf16 v[82:85], v[138:141], v[210:213], v[82:85]
	v_mfma_f32_16x16x32_bf16 v[126:129], v[142:145], v[182:185], v[126:129]
	v_mfma_f32_16x16x32_bf16 v[126:129], v[146:149], v[186:189], v[126:129]
	v_mfma_f32_16x16x32_bf16 v[110:113], v[142:145], v[190:193], v[110:113]
	v_mfma_f32_16x16x32_bf16 v[110:113], v[146:149], v[194:197], v[110:113]
	v_mfma_f32_16x16x32_bf16 v[94:97], v[142:145], v[198:201], v[94:97]
	v_mfma_f32_16x16x32_bf16 v[94:97], v[146:149], v[202:205], v[94:97]
	v_mfma_f32_16x16x32_bf16 v[78:81], v[142:145], v[206:209], v[78:81]
	v_mfma_f32_16x16x32_bf16 v[78:81], v[146:149], v[210:213], v[78:81]
	s_setprio 0
	s_setprio 1
	v_mfma_f32_16x16x32_bf16 v[122:125], v[150:153], v[182:185], v[122:125]
	v_mfma_f32_16x16x32_bf16 v[122:125], v[154:157], v[186:189], v[122:125]
	v_mfma_f32_16x16x32_bf16 v[106:109], v[150:153], v[190:193], v[106:109]
	v_mfma_f32_16x16x32_bf16 v[106:109], v[154:157], v[194:197], v[106:109]
	v_mfma_f32_16x16x32_bf16 v[90:93], v[150:153], v[198:201], v[90:93]
	v_mfma_f32_16x16x32_bf16 v[90:93], v[154:157], v[202:205], v[90:93]
	v_mfma_f32_16x16x32_bf16 v[74:77], v[150:153], v[206:209], v[74:77]
	v_mfma_f32_16x16x32_bf16 v[74:77], v[154:157], v[210:213], v[74:77]
	v_mfma_f32_16x16x32_bf16 v[118:121], v[174:177], v[182:185], v[118:121]
	v_mfma_f32_16x16x32_bf16 v[118:121], v[178:181], v[186:189], v[118:121]
	v_mfma_f32_16x16x32_bf16 v[102:105], v[174:177], v[190:193], v[102:105]
	v_mfma_f32_16x16x32_bf16 v[102:105], v[178:181], v[194:197], v[102:105]
	v_mfma_f32_16x16x32_bf16 v[86:89], v[174:177], v[198:201], v[86:89]
	v_mfma_f32_16x16x32_bf16 v[86:89], v[178:181], v[202:205], v[86:89]
	v_mfma_f32_16x16x32_bf16 v[70:73], v[174:177], v[206:209], v[70:73]
	v_mfma_f32_16x16x32_bf16 v[70:73], v[178:181], v[210:213], v[70:73]
	s_setprio 0
	s_barrier
	s_mov_b32 m0, s35
	s_mov_b32 s71, s51
	ds_read_b128 v[182:185], v172 offset:16384
	ds_read_b128 v[186:189], v172 offset:17408
	buffer_load_dwordx4 v166, s[68:71], s96 offen lds
	s_mov_b32 m0, s45
	ds_read_b128 v[190:193], v172 offset:18432
	ds_read_b128 v[194:197], v172 offset:19456
	buffer_load_dwordx4 v168, s[68:71], s96 offen lds
	s_add_i32 vcc_lo, s96, 0xc0000
	s_mov_b32 m0, s64
	ds_read_b128 v[198:201], v172 offset:20480
	ds_read_b128 v[202:205], v172 offset:21504
	buffer_load_dwordx4 v166, s[68:71], vcc_lo offen lds
	s_mov_b32 m0, s65
	ds_read_b128 v[206:209], v172 offset:22528
	ds_read_b128 v[210:213], v172 offset:23552
	buffer_load_dwordx4 v168, s[68:71], vcc_lo offen lds
	s_waitcnt vmcnt(6)
	s_waitcnt lgkmcnt(0)
	s_barrier
	s_setprio 1
	s_waitcnt lgkmcnt(0)
	v_mfma_f32_16x16x32_bf16 v[66:69], v[134:137], v[182:185], v[66:69]
	v_mfma_f32_16x16x32_bf16 v[66:69], v[138:141], v[186:189], v[66:69]
	v_mfma_f32_16x16x32_bf16 v[50:53], v[134:137], v[190:193], v[50:53]
	v_mfma_f32_16x16x32_bf16 v[50:53], v[138:141], v[194:197], v[50:53]
	v_mfma_f32_16x16x32_bf16 v[34:37], v[134:137], v[198:201], v[34:37]
	v_mfma_f32_16x16x32_bf16 v[34:37], v[138:141], v[202:205], v[34:37]
	v_mfma_f32_16x16x32_bf16 v[18:21], v[134:137], v[206:209], v[18:21]
	v_mfma_f32_16x16x32_bf16 v[18:21], v[138:141], v[210:213], v[18:21]
	v_mfma_f32_16x16x32_bf16 v[62:65], v[142:145], v[182:185], v[62:65]
	v_mfma_f32_16x16x32_bf16 v[62:65], v[146:149], v[186:189], v[62:65]
	v_mfma_f32_16x16x32_bf16 v[46:49], v[142:145], v[190:193], v[46:49]
	v_mfma_f32_16x16x32_bf16 v[46:49], v[146:149], v[194:197], v[46:49]
	v_mfma_f32_16x16x32_bf16 v[30:33], v[142:145], v[198:201], v[30:33]
	v_mfma_f32_16x16x32_bf16 v[30:33], v[146:149], v[202:205], v[30:33]
	v_mfma_f32_16x16x32_bf16 v[14:17], v[142:145], v[206:209], v[14:17]
	v_mfma_f32_16x16x32_bf16 v[14:17], v[146:149], v[210:213], v[14:17]
	s_setprio 0
	s_setprio 1
	v_mfma_f32_16x16x32_bf16 v[58:61], v[150:153], v[182:185], v[58:61]
	v_mfma_f32_16x16x32_bf16 v[58:61], v[154:157], v[186:189], v[58:61]
	v_mfma_f32_16x16x32_bf16 v[42:45], v[150:153], v[190:193], v[42:45]
	v_mfma_f32_16x16x32_bf16 v[42:45], v[154:157], v[194:197], v[42:45]
	v_mfma_f32_16x16x32_bf16 v[26:29], v[150:153], v[198:201], v[26:29]
	v_mfma_f32_16x16x32_bf16 v[26:29], v[154:157], v[202:205], v[26:29]
	v_mfma_f32_16x16x32_bf16 v[10:13], v[150:153], v[206:209], v[10:13]
	v_mfma_f32_16x16x32_bf16 v[10:13], v[154:157], v[210:213], v[10:13]
	v_mfma_f32_16x16x32_bf16 v[54:57], v[174:177], v[182:185], v[54:57]
	v_mfma_f32_16x16x32_bf16 v[54:57], v[178:181], v[186:189], v[54:57]
	v_mfma_f32_16x16x32_bf16 v[38:41], v[174:177], v[190:193], v[38:41]
	v_mfma_f32_16x16x32_bf16 v[38:41], v[178:181], v[194:197], v[38:41]
	v_mfma_f32_16x16x32_bf16 v[22:25], v[174:177], v[198:201], v[22:25]
	v_mfma_f32_16x16x32_bf16 v[22:25], v[178:181], v[202:205], v[22:25]
	v_mfma_f32_16x16x32_bf16 v[4:7], v[174:177], v[206:209], v[6:9]
	v_mfma_f32_16x16x32_bf16 v[4:7], v[178:181], v[210:213], v[4:7]
	s_setprio 0
	s_barrier
	v_add_u32_e32 v3, 0x18000, v171
	ds_read_b128 v[134:137], v3
	ds_read_b128 v[138:141], v3 offset:1024
	ds_read_b128 v[142:145], v3 offset:2048
	ds_read_b128 v[146:149], v3 offset:3072
	v_add_u32_e32 v3, 0x1c000, v171
	ds_read_b128 v[150:153], v3
	ds_read_b128 v[154:157], v3 offset:1024
	ds_read_b128 v[174:177], v3 offset:2048
	ds_read_b128 v[178:181], v3 offset:3072
	s_mov_b32 m0, s29
	ds_read_b128 v[182:185], v172 offset:32768
	ds_read_b128 v[186:189], v172 offset:33792
	buffer_load_dwordx4 v1, s[48:51], s97 offen lds
	s_mov_b32 m0, s66
	ds_read_b128 v[190:193], v172 offset:34816
	ds_read_b128 v[194:197], v172 offset:35840
	buffer_load_dwordx4 v167, s[48:51], s97 offen lds
	s_add_i32 s97, s97, 0xc0000
	s_mov_b32 m0, s67
	ds_read_b128 v[198:201], v172 offset:36864
	ds_read_b128 v[202:205], v172 offset:37888
	buffer_load_dwordx4 v1, s[48:51], s97 offen lds
	s_mov_b32 m0, s72
	ds_read_b128 v[206:209], v172 offset:38912
	ds_read_b128 v[210:213], v172 offset:39936
	buffer_load_dwordx4 v167, s[48:51], s97 offen lds
	s_waitcnt vmcnt(8)
	s_waitcnt lgkmcnt(0)
	s_barrier
	s_setprio 1
	s_waitcnt lgkmcnt(0)
	v_mfma_f32_16x16x32_bf16 v[130:133], v[134:137], v[182:185], v[130:133]
	v_mfma_f32_16x16x32_bf16 v[130:133], v[138:141], v[186:189], v[130:133]
	v_mfma_f32_16x16x32_bf16 v[114:117], v[134:137], v[190:193], v[114:117]
	v_mfma_f32_16x16x32_bf16 v[114:117], v[138:141], v[194:197], v[114:117]
	v_mfma_f32_16x16x32_bf16 v[98:101], v[134:137], v[198:201], v[98:101]
	v_mfma_f32_16x16x32_bf16 v[98:101], v[138:141], v[202:205], v[98:101]
	v_mfma_f32_16x16x32_bf16 v[82:85], v[134:137], v[206:209], v[82:85]
	v_mfma_f32_16x16x32_bf16 v[82:85], v[138:141], v[210:213], v[82:85]
	v_mfma_f32_16x16x32_bf16 v[126:129], v[142:145], v[182:185], v[126:129]
	v_mfma_f32_16x16x32_bf16 v[126:129], v[146:149], v[186:189], v[126:129]
	v_mfma_f32_16x16x32_bf16 v[110:113], v[142:145], v[190:193], v[110:113]
	v_mfma_f32_16x16x32_bf16 v[110:113], v[146:149], v[194:197], v[110:113]
	v_mfma_f32_16x16x32_bf16 v[94:97], v[142:145], v[198:201], v[94:97]
	v_mfma_f32_16x16x32_bf16 v[94:97], v[146:149], v[202:205], v[94:97]
	v_mfma_f32_16x16x32_bf16 v[78:81], v[142:145], v[206:209], v[78:81]
	v_mfma_f32_16x16x32_bf16 v[78:81], v[146:149], v[210:213], v[78:81]
	s_setprio 0
	s_setprio 1
	v_mfma_f32_16x16x32_bf16 v[122:125], v[150:153], v[182:185], v[122:125]
	v_mfma_f32_16x16x32_bf16 v[122:125], v[154:157], v[186:189], v[122:125]
	v_mfma_f32_16x16x32_bf16 v[106:109], v[150:153], v[190:193], v[106:109]
	v_mfma_f32_16x16x32_bf16 v[106:109], v[154:157], v[194:197], v[106:109]
	v_mfma_f32_16x16x32_bf16 v[90:93], v[150:153], v[198:201], v[90:93]
	v_mfma_f32_16x16x32_bf16 v[90:93], v[154:157], v[202:205], v[90:93]
	v_mfma_f32_16x16x32_bf16 v[74:77], v[150:153], v[206:209], v[74:77]
	v_mfma_f32_16x16x32_bf16 v[74:77], v[154:157], v[210:213], v[74:77]
	v_mfma_f32_16x16x32_bf16 v[118:121], v[174:177], v[182:185], v[118:121]
	v_mfma_f32_16x16x32_bf16 v[118:121], v[178:181], v[186:189], v[118:121]
	v_mfma_f32_16x16x32_bf16 v[102:105], v[174:177], v[190:193], v[102:105]
	v_mfma_f32_16x16x32_bf16 v[102:105], v[178:181], v[194:197], v[102:105]
	v_mfma_f32_16x16x32_bf16 v[86:89], v[174:177], v[198:201], v[86:89]
	v_mfma_f32_16x16x32_bf16 v[86:89], v[178:181], v[202:205], v[86:89]
	v_mfma_f32_16x16x32_bf16 v[70:73], v[174:177], v[206:209], v[70:73]
	v_mfma_f32_16x16x32_bf16 v[70:73], v[178:181], v[210:213], v[70:73]
	s_setprio 0
	s_barrier
	s_mov_b32 m0, s74
	s_add_i32 s97, s96, 0x80
	ds_read_b128 v[182:185], v172 offset:49152
	ds_read_b128 v[186:189], v172 offset:50176
	buffer_load_dwordx4 v166, s[68:71], s97 offen lds
	s_mov_b32 m0, s75
	ds_read_b128 v[190:193], v172 offset:51200
	ds_read_b128 v[194:197], v172 offset:52224
	buffer_load_dwordx4 v168, s[68:71], s97 offen lds
	s_add_i32 s96, s96, 0xc0080
	s_mov_b32 m0, s77
	ds_read_b128 v[198:201], v172 offset:53248
	ds_read_b128 v[202:205], v172 offset:54272
	buffer_load_dwordx4 v166, s[68:71], s96 offen lds
	s_mov_b32 m0, s78
	ds_read_b128 v[206:209], v172 offset:55296
	ds_read_b128 v[210:213], v172 offset:56320
	buffer_load_dwordx4 v168, s[68:71], s96 offen lds
	s_waitcnt vmcnt(6)
	s_waitcnt lgkmcnt(0)
	s_barrier
	s_setprio 1
	s_waitcnt lgkmcnt(0)
	v_mfma_f32_16x16x32_bf16 v[66:69], v[134:137], v[182:185], v[66:69]
	v_mfma_f32_16x16x32_bf16 v[66:69], v[138:141], v[186:189], v[66:69]
	v_mfma_f32_16x16x32_bf16 v[50:53], v[134:137], v[190:193], v[50:53]
	v_mfma_f32_16x16x32_bf16 v[50:53], v[138:141], v[194:197], v[50:53]
	v_mfma_f32_16x16x32_bf16 v[34:37], v[134:137], v[198:201], v[34:37]
	v_mfma_f32_16x16x32_bf16 v[34:37], v[138:141], v[202:205], v[34:37]
	v_mfma_f32_16x16x32_bf16 v[18:21], v[134:137], v[206:209], v[18:21]
	v_mfma_f32_16x16x32_bf16 v[18:21], v[138:141], v[210:213], v[18:21]
	v_mfma_f32_16x16x32_bf16 v[62:65], v[142:145], v[182:185], v[62:65]
	v_mfma_f32_16x16x32_bf16 v[62:65], v[146:149], v[186:189], v[62:65]
	v_mfma_f32_16x16x32_bf16 v[46:49], v[142:145], v[190:193], v[46:49]
	v_mfma_f32_16x16x32_bf16 v[46:49], v[146:149], v[194:197], v[46:49]
	v_mfma_f32_16x16x32_bf16 v[30:33], v[142:145], v[198:201], v[30:33]
	v_mfma_f32_16x16x32_bf16 v[30:33], v[146:149], v[202:205], v[30:33]
	v_mfma_f32_16x16x32_bf16 v[14:17], v[142:145], v[206:209], v[14:17]
	v_mfma_f32_16x16x32_bf16 v[14:17], v[146:149], v[210:213], v[14:17]
	s_setprio 0
	s_setprio 1
	v_mfma_f32_16x16x32_bf16 v[58:61], v[150:153], v[182:185], v[58:61]
	v_mfma_f32_16x16x32_bf16 v[58:61], v[154:157], v[186:189], v[58:61]
	v_mfma_f32_16x16x32_bf16 v[42:45], v[150:153], v[190:193], v[42:45]
	v_mfma_f32_16x16x32_bf16 v[42:45], v[154:157], v[194:197], v[42:45]
	v_mfma_f32_16x16x32_bf16 v[26:29], v[150:153], v[198:201], v[26:29]
	v_mfma_f32_16x16x32_bf16 v[26:29], v[154:157], v[202:205], v[26:29]
	v_mfma_f32_16x16x32_bf16 v[8:11], v[150:153], v[206:209], v[10:13]
	v_mfma_f32_16x16x32_bf16 v[10:13], v[154:157], v[210:213], v[8:11]
	v_mfma_f32_16x16x32_bf16 v[54:57], v[174:177], v[182:185], v[54:57]
	v_mfma_f32_16x16x32_bf16 v[54:57], v[178:181], v[186:189], v[54:57]
	v_mfma_f32_16x16x32_bf16 v[38:41], v[174:177], v[190:193], v[38:41]
	v_mfma_f32_16x16x32_bf16 v[38:41], v[178:181], v[194:197], v[38:41]
	v_mfma_f32_16x16x32_bf16 v[22:25], v[174:177], v[198:201], v[22:25]
	v_mfma_f32_16x16x32_bf16 v[22:25], v[178:181], v[202:205], v[22:25]
	v_mfma_f32_16x16x32_bf16 v[4:7], v[174:177], v[206:209], v[4:7]
	v_mfma_f32_16x16x32_bf16 v[6:9], v[178:181], v[210:213], v[4:7]
	s_setprio 0
	s_barrier
	s_add_i32 s92, s92, 2
	s_addk_i32 s95, 0x100
	s_addk_i32 s94, 0x100
	s_addk_i32 s93, 0xff00
	s_cmp_ge_u32 s92, s62
	s_cbranch_scc0 .LBB0_528
	s_branch .LBB0_523

.LBB0_605:
	v_add_u32_e32 v141, 0x10000, v139
	ds_read_b128 v[142:145], v141
	ds_read_b128 v[146:149], v141 offset:1024
	ds_read_b128 v[154:157], v141 offset:2048
	ds_read_b128 v[158:161], v141 offset:3072
	v_add_u32_e32 v141, 0x14000, v139
	ds_read_b128 v[162:165], v141
	ds_read_b128 v[166:169], v141 offset:1024
	ds_read_b128 v[170:173], v141 offset:2048
	ds_read_b128 v[174:177], v141 offset:3072
	s_add_i32 s47, s64, s82
	s_add_i32 s84, s47, 0x100
	s_add_i32 s83, s11, s82
	s_cmpk_eq_i32 s82, 0xf00
	s_cselect_b32 s83, s80, s83
	s_cselect_b32 s84, s79, s84
	s_add_i32 s85, s47, 0x80
	s_mov_b32 m0, s71
	ds_read_b128 v[178:181], v140
	ds_read_b128 v[182:185], v140 offset:1024
	buffer_load_dwordx4 v135, s[12:15], s85 offen lds
	s_mov_b32 m0, s72
	ds_read_b128 v[186:189], v140 offset:2048
	ds_read_b128 v[190:193], v140 offset:3072
	buffer_load_dwordx4 v137, s[12:15], s85 offen lds
	s_add_i32 s47, s47, 0x80080
	s_mov_b32 m0, s73
	ds_read_b128 v[194:197], v140 offset:4096
	ds_read_b128 v[198:201], v140 offset:5120
	buffer_load_dwordx4 v135, s[12:15], s47 offen lds
	s_mov_b32 m0, s74
	ds_read_b128 v[202:205], v140 offset:6144
	ds_read_b128 v[206:209], v140 offset:7168
	buffer_load_dwordx4 v137, s[12:15], s47 offen lds
	s_waitcnt vmcnt(8)
	s_waitcnt lgkmcnt(0)
	s_barrier
	s_setprio 1
	s_waitcnt lgkmcnt(0)
	v_mfma_f32_16x16x32_bf16 v[126:129], v[142:145], v[178:181], v[126:129]
	v_mfma_f32_16x16x32_bf16 v[126:129], v[146:149], v[182:185], v[126:129]
	v_mfma_f32_16x16x32_bf16 v[110:113], v[142:145], v[186:189], v[110:113]
	v_mfma_f32_16x16x32_bf16 v[110:113], v[146:149], v[190:193], v[110:113]
	v_mfma_f32_16x16x32_bf16 v[94:97], v[142:145], v[194:197], v[94:97]
	v_mfma_f32_16x16x32_bf16 v[94:97], v[146:149], v[198:201], v[94:97]
	v_mfma_f32_16x16x32_bf16 v[78:81], v[142:145], v[202:205], v[78:81]
	v_mfma_f32_16x16x32_bf16 v[78:81], v[146:149], v[206:209], v[78:81]
	v_mfma_f32_16x16x32_bf16 v[122:125], v[154:157], v[178:181], v[122:125]
	v_mfma_f32_16x16x32_bf16 v[122:125], v[158:161], v[182:185], v[122:125]
	v_mfma_f32_16x16x32_bf16 v[106:109], v[154:157], v[186:189], v[106:109]
	v_mfma_f32_16x16x32_bf16 v[106:109], v[158:161], v[190:193], v[106:109]
	v_mfma_f32_16x16x32_bf16 v[90:93], v[154:157], v[194:197], v[90:93]
	v_mfma_f32_16x16x32_bf16 v[90:93], v[158:161], v[198:201], v[90:93]
	v_mfma_f32_16x16x32_bf16 v[74:77], v[154:157], v[202:205], v[74:77]
	v_mfma_f32_16x16x32_bf16 v[74:77], v[158:161], v[206:209], v[74:77]
	s_setprio 0
	s_setprio 1
	v_mfma_f32_16x16x32_bf16 v[118:121], v[162:165], v[178:181], v[118:121]
	v_mfma_f32_16x16x32_bf16 v[118:121], v[166:169], v[182:185], v[118:121]
	v_mfma_f32_16x16x32_bf16 v[102:105], v[162:165], v[186:189], v[102:105]
	v_mfma_f32_16x16x32_bf16 v[102:105], v[166:169], v[190:193], v[102:105]
	v_mfma_f32_16x16x32_bf16 v[86:89], v[162:165], v[194:197], v[86:89]
	v_mfma_f32_16x16x32_bf16 v[86:89], v[166:169], v[198:201], v[86:89]
	v_mfma_f32_16x16x32_bf16 v[70:73], v[162:165], v[202:205], v[70:73]
	v_mfma_f32_16x16x32_bf16 v[70:73], v[166:169], v[206:209], v[70:73]
	v_mfma_f32_16x16x32_bf16 v[114:117], v[170:173], v[178:181], v[114:117]
	v_mfma_f32_16x16x32_bf16 v[114:117], v[174:177], v[182:185], v[114:117]
	v_mfma_f32_16x16x32_bf16 v[98:101], v[170:173], v[186:189], v[98:101]
	v_mfma_f32_16x16x32_bf16 v[98:101], v[174:177], v[190:193], v[98:101]
	v_mfma_f32_16x16x32_bf16 v[82:85], v[170:173], v[194:197], v[82:85]
	v_mfma_f32_16x16x32_bf16 v[82:85], v[174:177], v[198:201], v[82:85]
	v_mfma_f32_16x16x32_bf16 v[66:69], v[170:173], v[202:205], v[66:69]
	v_mfma_f32_16x16x32_bf16 v[66:69], v[174:177], v[206:209], v[66:69]
	s_setprio 0
	s_barrier
	s_mov_b32 m0, s58
	s_mov_b32 s47, s15
	ds_read_b128 v[178:181], v140 offset:16384
	ds_read_b128 v[182:185], v140 offset:17408
	buffer_load_dwordx4 v136, s[44:47], s83 offen lds
	s_mov_b32 m0, s60
	ds_read_b128 v[186:189], v140 offset:18432
	ds_read_b128 v[190:193], v140 offset:19456
	buffer_load_dwordx4 v138, s[44:47], s83 offen lds
	s_add_i32 s85, s83, 0x80000
	s_mov_b32 m0, s61
	ds_read_b128 v[194:197], v140 offset:20480
	ds_read_b128 v[198:201], v140 offset:21504
	buffer_load_dwordx4 v136, s[44:47], s85 offen lds
	s_mov_b32 m0, s62
	ds_read_b128 v[202:205], v140 offset:22528
	ds_read_b128 v[206:209], v140 offset:23552
	buffer_load_dwordx4 v138, s[44:47], s85 offen lds
	s_waitcnt vmcnt(6)
	s_waitcnt lgkmcnt(0)
	s_barrier
	s_setprio 1
	s_waitcnt lgkmcnt(0)
	v_mfma_f32_16x16x32_bf16 v[62:65], v[142:145], v[178:181], v[62:65]
	v_mfma_f32_16x16x32_bf16 v[62:65], v[146:149], v[182:185], v[62:65]
	v_mfma_f32_16x16x32_bf16 v[46:49], v[142:145], v[186:189], v[46:49]
	v_mfma_f32_16x16x32_bf16 v[46:49], v[146:149], v[190:193], v[46:49]
	v_mfma_f32_16x16x32_bf16 v[30:33], v[142:145], v[194:197], v[30:33]
	v_mfma_f32_16x16x32_bf16 v[30:33], v[146:149], v[198:201], v[30:33]
	v_mfma_f32_16x16x32_bf16 v[14:17], v[142:145], v[202:205], v[14:17]
	v_mfma_f32_16x16x32_bf16 v[14:17], v[146:149], v[206:209], v[14:17]
	v_mfma_f32_16x16x32_bf16 v[58:61], v[154:157], v[178:181], v[58:61]
	v_mfma_f32_16x16x32_bf16 v[58:61], v[158:161], v[182:185], v[58:61]
	v_mfma_f32_16x16x32_bf16 v[42:45], v[154:157], v[186:189], v[42:45]
	v_mfma_f32_16x16x32_bf16 v[42:45], v[158:161], v[190:193], v[42:45]
	v_mfma_f32_16x16x32_bf16 v[26:29], v[154:157], v[194:197], v[26:29]
	v_mfma_f32_16x16x32_bf16 v[26:29], v[158:161], v[198:201], v[26:29]
	v_mfma_f32_16x16x32_bf16 v[10:13], v[154:157], v[202:205], v[10:13]
	v_mfma_f32_16x16x32_bf16 v[10:13], v[158:161], v[206:209], v[10:13]
	s_setprio 0
	s_setprio 1
	v_mfma_f32_16x16x32_bf16 v[54:57], v[162:165], v[178:181], v[54:57]
	v_mfma_f32_16x16x32_bf16 v[54:57], v[166:169], v[182:185], v[54:57]
	v_mfma_f32_16x16x32_bf16 v[38:41], v[162:165], v[186:189], v[38:41]
	v_mfma_f32_16x16x32_bf16 v[38:41], v[166:169], v[190:193], v[38:41]
	v_mfma_f32_16x16x32_bf16 v[22:25], v[162:165], v[194:197], v[22:25]
	v_mfma_f32_16x16x32_bf16 v[22:25], v[166:169], v[198:201], v[22:25]
	v_mfma_f32_16x16x32_bf16 v[6:9], v[162:165], v[202:205], v[6:9]
	v_mfma_f32_16x16x32_bf16 v[6:9], v[166:169], v[206:209], v[6:9]
	v_mfma_f32_16x16x32_bf16 v[50:53], v[170:173], v[178:181], v[50:53]
	v_mfma_f32_16x16x32_bf16 v[50:53], v[174:177], v[182:185], v[50:53]
	v_mfma_f32_16x16x32_bf16 v[34:37], v[170:173], v[186:189], v[34:37]
	v_mfma_f32_16x16x32_bf16 v[34:37], v[174:177], v[190:193], v[34:37]
	v_mfma_f32_16x16x32_bf16 v[18:21], v[170:173], v[194:197], v[18:21]
	v_mfma_f32_16x16x32_bf16 v[18:21], v[174:177], v[198:201], v[18:21]
	v_mfma_f32_16x16x32_bf16 v[2:5], v[170:173], v[202:205], v[2:5]
	v_mfma_f32_16x16x32_bf16 v[2:5], v[174:177], v[206:209], v[2:5]
	s_setprio 0
	s_barrier
	v_add_u32_e32 v141, 0x18000, v139
	ds_read_b128 v[142:145], v141
	ds_read_b128 v[146:149], v141 offset:1024
	ds_read_b128 v[154:157], v141 offset:2048
	ds_read_b128 v[158:161], v141 offset:3072
	v_add_u32_e32 v141, 0x1c000, v139
	ds_read_b128 v[162:165], v141
	ds_read_b128 v[166:169], v141 offset:1024
	ds_read_b128 v[170:173], v141 offset:2048
	ds_read_b128 v[174:177], v141 offset:3072
	s_mov_b32 m0, s51
	ds_read_b128 v[178:181], v140 offset:32768
	ds_read_b128 v[182:185], v140 offset:33792
	buffer_load_dwordx4 v135, s[12:15], s84 offen lds
	s_mov_b32 m0, s63
	ds_read_b128 v[186:189], v140 offset:34816
	ds_read_b128 v[190:193], v140 offset:35840
	buffer_load_dwordx4 v137, s[12:15], s84 offen lds
	s_add_i32 s84, s84, 0x80000
	s_mov_b32 m0, s65
	ds_read_b128 v[194:197], v140 offset:36864
	ds_read_b128 v[198:201], v140 offset:37888
	buffer_load_dwordx4 v135, s[12:15], s84 offen lds
	s_mov_b32 m0, s66
	ds_read_b128 v[202:205], v140 offset:38912
	ds_read_b128 v[206:209], v140 offset:39936
	buffer_load_dwordx4 v137, s[12:15], s84 offen lds
	s_waitcnt vmcnt(8)
	s_waitcnt lgkmcnt(0)
	s_barrier
	s_setprio 1
	s_waitcnt lgkmcnt(0)
	v_mfma_f32_16x16x32_bf16 v[126:129], v[142:145], v[178:181], v[126:129]
	v_mfma_f32_16x16x32_bf16 v[126:129], v[146:149], v[182:185], v[126:129]
	v_mfma_f32_16x16x32_bf16 v[110:113], v[142:145], v[186:189], v[110:113]
	v_mfma_f32_16x16x32_bf16 v[110:113], v[146:149], v[190:193], v[110:113]
	v_mfma_f32_16x16x32_bf16 v[94:97], v[142:145], v[194:197], v[94:97]
	v_mfma_f32_16x16x32_bf16 v[94:97], v[146:149], v[198:201], v[94:97]
	v_mfma_f32_16x16x32_bf16 v[78:81], v[142:145], v[202:205], v[78:81]
	v_mfma_f32_16x16x32_bf16 v[78:81], v[146:149], v[206:209], v[78:81]
	v_mfma_f32_16x16x32_bf16 v[122:125], v[154:157], v[178:181], v[122:125]
	v_mfma_f32_16x16x32_bf16 v[122:125], v[158:161], v[182:185], v[122:125]
	v_mfma_f32_16x16x32_bf16 v[106:109], v[154:157], v[186:189], v[106:109]
	v_mfma_f32_16x16x32_bf16 v[106:109], v[158:161], v[190:193], v[106:109]
	v_mfma_f32_16x16x32_bf16 v[90:93], v[154:157], v[194:197], v[90:93]
	v_mfma_f32_16x16x32_bf16 v[90:93], v[158:161], v[198:201], v[90:93]
	v_mfma_f32_16x16x32_bf16 v[74:77], v[154:157], v[202:205], v[74:77]
	v_mfma_f32_16x16x32_bf16 v[74:77], v[158:161], v[206:209], v[74:77]
	s_setprio 0
	s_setprio 1
	v_mfma_f32_16x16x32_bf16 v[118:121], v[162:165], v[178:181], v[118:121]
	v_mfma_f32_16x16x32_bf16 v[118:121], v[166:169], v[182:185], v[118:121]
	v_mfma_f32_16x16x32_bf16 v[102:105], v[162:165], v[186:189], v[102:105]
	v_mfma_f32_16x16x32_bf16 v[102:105], v[166:169], v[190:193], v[102:105]
	v_mfma_f32_16x16x32_bf16 v[86:89], v[162:165], v[194:197], v[86:89]
	v_mfma_f32_16x16x32_bf16 v[86:89], v[166:169], v[198:201], v[86:89]
	v_mfma_f32_16x16x32_bf16 v[70:73], v[162:165], v[202:205], v[70:73]
	v_mfma_f32_16x16x32_bf16 v[70:73], v[166:169], v[206:209], v[70:73]
	v_mfma_f32_16x16x32_bf16 v[114:117], v[170:173], v[178:181], v[114:117]
	v_mfma_f32_16x16x32_bf16 v[114:117], v[174:177], v[182:185], v[114:117]
	v_mfma_f32_16x16x32_bf16 v[98:101], v[170:173], v[186:189], v[98:101]
	v_mfma_f32_16x16x32_bf16 v[98:101], v[174:177], v[190:193], v[98:101]
	v_mfma_f32_16x16x32_bf16 v[82:85], v[170:173], v[194:197], v[82:85]
	v_mfma_f32_16x16x32_bf16 v[82:85], v[174:177], v[198:201], v[82:85]
	v_mfma_f32_16x16x32_bf16 v[66:69], v[170:173], v[202:205], v[66:69]
	v_mfma_f32_16x16x32_bf16 v[66:69], v[174:177], v[206:209], v[66:69]
	s_setprio 0
	s_barrier
	s_mov_b32 m0, s67
	s_or_b32 s84, s83, 0x80
	ds_read_b128 v[178:181], v140 offset:49152
	ds_read_b128 v[182:185], v140 offset:50176
	buffer_load_dwordx4 v136, s[44:47], s84 offen lds
	s_mov_b32 m0, s68
	ds_read_b128 v[186:189], v140 offset:51200
	ds_read_b128 v[190:193], v140 offset:52224
	buffer_load_dwordx4 v138, s[44:47], s84 offen lds
	s_add_i32 s83, s83, 0x80080
	s_mov_b32 m0, s69
	ds_read_b128 v[194:197], v140 offset:53248
	ds_read_b128 v[198:201], v140 offset:54272
	buffer_load_dwordx4 v136, s[44:47], s83 offen lds
	s_mov_b32 m0, s70
	ds_read_b128 v[202:205], v140 offset:55296
	ds_read_b128 v[206:209], v140 offset:56320
	buffer_load_dwordx4 v138, s[44:47], s83 offen lds
	s_waitcnt vmcnt(6)
	s_waitcnt lgkmcnt(0)
	s_barrier
	s_setprio 1
	s_waitcnt lgkmcnt(0)
	v_mfma_f32_16x16x32_bf16 v[62:65], v[142:145], v[178:181], v[62:65]
	v_mfma_f32_16x16x32_bf16 v[62:65], v[146:149], v[182:185], v[62:65]
	v_mfma_f32_16x16x32_bf16 v[46:49], v[142:145], v[186:189], v[46:49]
	v_mfma_f32_16x16x32_bf16 v[46:49], v[146:149], v[190:193], v[46:49]
	v_mfma_f32_16x16x32_bf16 v[30:33], v[142:145], v[194:197], v[30:33]
	v_mfma_f32_16x16x32_bf16 v[30:33], v[146:149], v[198:201], v[30:33]
	v_mfma_f32_16x16x32_bf16 v[14:17], v[142:145], v[202:205], v[14:17]
	v_mfma_f32_16x16x32_bf16 v[14:17], v[146:149], v[206:209], v[14:17]
	v_mfma_f32_16x16x32_bf16 v[58:61], v[154:157], v[178:181], v[58:61]
	v_mfma_f32_16x16x32_bf16 v[58:61], v[158:161], v[182:185], v[58:61]
	v_mfma_f32_16x16x32_bf16 v[42:45], v[154:157], v[186:189], v[42:45]
	v_mfma_f32_16x16x32_bf16 v[42:45], v[158:161], v[190:193], v[42:45]
	v_mfma_f32_16x16x32_bf16 v[26:29], v[154:157], v[194:197], v[26:29]
	v_mfma_f32_16x16x32_bf16 v[26:29], v[158:161], v[198:201], v[26:29]
	v_mfma_f32_16x16x32_bf16 v[10:13], v[154:157], v[202:205], v[10:13]
	v_mfma_f32_16x16x32_bf16 v[10:13], v[158:161], v[206:209], v[10:13]
	s_setprio 0
	s_setprio 1
	v_mfma_f32_16x16x32_bf16 v[54:57], v[162:165], v[178:181], v[54:57]
	v_mfma_f32_16x16x32_bf16 v[54:57], v[166:169], v[182:185], v[54:57]
	v_mfma_f32_16x16x32_bf16 v[38:41], v[162:165], v[186:189], v[38:41]
	v_mfma_f32_16x16x32_bf16 v[38:41], v[166:169], v[190:193], v[38:41]
	v_mfma_f32_16x16x32_bf16 v[22:25], v[162:165], v[194:197], v[22:25]
	v_mfma_f32_16x16x32_bf16 v[22:25], v[166:169], v[198:201], v[22:25]
	v_mfma_f32_16x16x32_bf16 v[6:9], v[162:165], v[202:205], v[6:9]
	v_mfma_f32_16x16x32_bf16 v[6:9], v[166:169], v[206:209], v[6:9]
	v_mfma_f32_16x16x32_bf16 v[50:53], v[170:173], v[178:181], v[50:53]
	v_mfma_f32_16x16x32_bf16 v[50:53], v[174:177], v[182:185], v[50:53]
	v_mfma_f32_16x16x32_bf16 v[34:37], v[170:173], v[186:189], v[34:37]
	v_mfma_f32_16x16x32_bf16 v[34:37], v[174:177], v[190:193], v[34:37]
	v_mfma_f32_16x16x32_bf16 v[18:21], v[170:173], v[194:197], v[18:21]
	v_mfma_f32_16x16x32_bf16 v[18:21], v[174:177], v[198:201], v[18:21]
	v_mfma_f32_16x16x32_bf16 v[2:5], v[170:173], v[202:205], v[2:5]
	v_mfma_f32_16x16x32_bf16 v[2:5], v[174:177], v[206:209], v[2:5]
	s_setprio 0
	s_barrier
	s_add_i32 s81, s81, 2
	s_addk_i32 s82, 0x100
	s_cmp_gt_u32 s81, 29
	s_cbranch_scc0 .LBB0_605
	s_andn2_b64 vcc, exec, s[4:5]
	s_cbranch_vccnz .LBB0_597
	v_mov_b32_e32 v2, 0
	s_mov_b32 s42, s77
	s_mov_b32 s3, s78
	s_mov_b32 s59, s10
	s_mov_b32 s64, s9
	s_mov_b32 s75, s8
	v_mov_b32_e32 v3, v2
	v_mov_b32_e32 v4, v2
	v_mov_b32_e32 v5, v2
	v_mov_b32_e32 v6, v2
	v_mov_b32_e32 v7, v2
	v_mov_b32_e32 v8, v2
	v_mov_b32_e32 v9, v2
	v_mov_b32_e32 v18, v2
	v_mov_b32_e32 v19, v2
	v_mov_b32_e32 v20, v2
	v_mov_b32_e32 v21, v2
	v_mov_b32_e32 v22, v2
	v_mov_b32_e32 v23, v2
	v_mov_b32_e32 v24, v2
	v_mov_b32_e32 v25, v2
	v_mov_b32_e32 v34, v2
	v_mov_b32_e32 v35, v2
	v_mov_b32_e32 v36, v2
	v_mov_b32_e32 v37, v2
	v_mov_b32_e32 v38, v2
	v_mov_b32_e32 v39, v2
	v_mov_b32_e32 v40, v2
	v_mov_b32_e32 v41, v2
	v_mov_b32_e32 v50, v2
	v_mov_b32_e32 v51, v2
	v_mov_b32_e32 v52, v2
	v_mov_b32_e32 v53, v2
	v_mov_b32_e32 v54, v2
	v_mov_b32_e32 v55, v2
	v_mov_b32_e32 v56, v2
	v_mov_b32_e32 v57, v2
	v_mov_b32_e32 v10, v2
	v_mov_b32_e32 v11, v2
	v_mov_b32_e32 v12, v2
	v_mov_b32_e32 v13, v2
	v_mov_b32_e32 v14, v2
	v_mov_b32_e32 v15, v2
	v_mov_b32_e32 v16, v2
	v_mov_b32_e32 v17, v2
	v_mov_b32_e32 v26, v2
	v_mov_b32_e32 v27, v2
	v_mov_b32_e32 v28, v2
	v_mov_b32_e32 v29, v2
	v_mov_b32_e32 v30, v2
	v_mov_b32_e32 v31, v2
	v_mov_b32_e32 v32, v2
	v_mov_b32_e32 v33, v2
	v_mov_b32_e32 v42, v2
	v_mov_b32_e32 v43, v2
	v_mov_b32_e32 v44, v2
	v_mov_b32_e32 v45, v2
	v_mov_b32_e32 v46, v2
	v_mov_b32_e32 v47, v2
	v_mov_b32_e32 v48, v2
	v_mov_b32_e32 v49, v2
	v_mov_b32_e32 v58, v2
	v_mov_b32_e32 v59, v2
	v_mov_b32_e32 v60, v2
	v_mov_b32_e32 v61, v2
	v_mov_b32_e32 v62, v2
	v_mov_b32_e32 v63, v2
	v_mov_b32_e32 v64, v2
	v_mov_b32_e32 v65, v2
	v_mov_b32_e32 v66, v2
	v_mov_b32_e32 v67, v2
	v_mov_b32_e32 v68, v2
	v_mov_b32_e32 v69, v2
	v_mov_b32_e32 v70, v2
	v_mov_b32_e32 v71, v2
	v_mov_b32_e32 v72, v2
	v_mov_b32_e32 v73, v2
	v_mov_b32_e32 v82, v2
	v_mov_b32_e32 v83, v2
	v_mov_b32_e32 v84, v2
	v_mov_b32_e32 v85, v2
	v_mov_b32_e32 v86, v2
	v_mov_b32_e32 v87, v2
	v_mov_b32_e32 v88, v2
	v_mov_b32_e32 v89, v2
	v_mov_b32_e32 v98, v2
	v_mov_b32_e32 v99, v2
	v_mov_b32_e32 v100, v2
	v_mov_b32_e32 v101, v2
	v_mov_b32_e32 v102, v2
	v_mov_b32_e32 v103, v2
	v_mov_b32_e32 v104, v2
	v_mov_b32_e32 v105, v2
	v_mov_b32_e32 v114, v2
	v_mov_b32_e32 v115, v2
	v_mov_b32_e32 v116, v2
	v_mov_b32_e32 v117, v2
	v_mov_b32_e32 v118, v2
	v_mov_b32_e32 v119, v2
	v_mov_b32_e32 v120, v2
	v_mov_b32_e32 v121, v2
	v_mov_b32_e32 v74, v2
	v_mov_b32_e32 v75, v2
	v_mov_b32_e32 v76, v2
	v_mov_b32_e32 v77, v2
	v_mov_b32_e32 v78, v2
	v_mov_b32_e32 v79, v2
	v_mov_b32_e32 v80, v2
	v_mov_b32_e32 v81, v2
	v_mov_b32_e32 v90, v2
	v_mov_b32_e32 v91, v2
	v_mov_b32_e32 v92, v2
	v_mov_b32_e32 v93, v2
	v_mov_b32_e32 v94, v2
	v_mov_b32_e32 v95, v2
	v_mov_b32_e32 v96, v2
	v_mov_b32_e32 v97, v2
	v_mov_b32_e32 v106, v2
	v_mov_b32_e32 v107, v2
	v_mov_b32_e32 v108, v2
	v_mov_b32_e32 v109, v2
	v_mov_b32_e32 v110, v2
	v_mov_b32_e32 v111, v2
	v_mov_b32_e32 v112, v2
	v_mov_b32_e32 v113, v2
	v_mov_b32_e32 v122, v2
	v_mov_b32_e32 v123, v2
	v_mov_b32_e32 v124, v2
	v_mov_b32_e32 v125, v2
	v_mov_b32_e32 v126, v2
	v_mov_b32_e32 v127, v2
	v_mov_b32_e32 v128, v2
	v_mov_b32_e32 v129, v2
	s_branch .LBB0_597

.LBB0_822:
	ds_read_b128 v[66:69], v242
	ds_read_b128 v[70:73], v242 offset:1024
	ds_read_b128 v[74:77], v242 offset:2048
	ds_read_b128 v[78:81], v242 offset:3072
	ds_read_b128 v[82:85], v243
	ds_read_b128 v[86:89], v243 offset:1024
	ds_read_b128 v[90:93], v243 offset:2048
	ds_read_b128 v[94:97], v243 offset:3072
	s_add_i32 s43, s68, 0xfff80080
	s_cmp_eq_u32 s69, 28
	s_cselect_b32 s91, s11, s67
	s_cselect_b32 s92, s10, s43
	s_add_i32 s43, s68, 0xfff80000
	s_mov_b32 m0, s79
	ds_read_b128 v[98:101], v244
	ds_read_b128 v[102:105], v244 offset:1024
	buffer_load_dwordx4 v1, s[48:51], s43 offen lds
	s_mov_b32 m0, s80
	ds_read_b128 v[106:109], v244 offset:2048
	ds_read_b128 v[110:113], v244 offset:3072
	buffer_load_dwordx4 v236, s[48:51], s43 offen lds
	s_mov_b32 m0, s81
	ds_read_b128 v[114:117], v244 offset:4096
	ds_read_b128 v[118:121], v244 offset:5120
	buffer_load_dwordx4 v1, s[48:51], s68 offen lds
	s_mov_b32 m0, s82
	ds_read_b128 v[122:125], v244 offset:6144
	ds_read_b128 v[126:129], v244 offset:7168
	buffer_load_dwordx4 v236, s[48:51], s68 offen lds
	s_waitcnt vmcnt(8)
	s_waitcnt lgkmcnt(0)
	s_barrier
	s_setprio 1
	s_waitcnt lgkmcnt(0)
	v_mfma_f32_16x16x32_bf16 v[190:193], v[66:69], v[98:101], v[190:193]
	v_mfma_f32_16x16x32_bf16 v[190:193], v[70:73], v[102:105], v[190:193]
	v_mfma_f32_16x16x32_bf16 v[174:177], v[66:69], v[106:109], v[174:177]
	v_mfma_f32_16x16x32_bf16 v[174:177], v[70:73], v[110:113], v[174:177]
	v_mfma_f32_16x16x32_bf16 v[170:173], v[66:69], v[114:117], v[170:173]
	v_mfma_f32_16x16x32_bf16 v[170:173], v[70:73], v[118:121], v[170:173]
	v_mfma_f32_16x16x32_bf16 v[158:161], v[66:69], v[122:125], v[158:161]
	v_mfma_f32_16x16x32_bf16 v[158:161], v[70:73], v[126:129], v[158:161]
	v_mfma_f32_16x16x32_bf16 v[186:189], v[74:77], v[98:101], v[186:189]
	v_mfma_f32_16x16x32_bf16 v[186:189], v[78:81], v[102:105], v[186:189]
	v_mfma_f32_16x16x32_bf16 v[166:169], v[74:77], v[106:109], v[166:169]
	v_mfma_f32_16x16x32_bf16 v[166:169], v[78:81], v[110:113], v[166:169]
	v_mfma_f32_16x16x32_bf16 v[162:165], v[74:77], v[114:117], v[162:165]
	v_mfma_f32_16x16x32_bf16 v[162:165], v[78:81], v[118:121], v[162:165]
	v_mfma_f32_16x16x32_bf16 v[154:157], v[74:77], v[122:125], v[154:157]
	v_mfma_f32_16x16x32_bf16 v[154:157], v[78:81], v[126:129], v[154:157]
	s_setprio 0
	s_setprio 1
	v_mfma_f32_16x16x32_bf16 v[182:185], v[82:85], v[98:101], v[182:185]
	v_mfma_f32_16x16x32_bf16 v[182:185], v[86:89], v[102:105], v[182:185]
	v_mfma_f32_16x16x32_bf16 v[98:101], v[90:93], v[98:101], v[178:181]
	v_mfma_f32_16x16x32_bf16 v[98:101], v[94:97], v[102:105], v[98:101]
	v_mfma_f32_16x16x32_bf16 v[102:105], v[82:85], v[106:109], v[150:153]
	v_mfma_f32_16x16x32_bf16 v[102:105], v[86:89], v[110:113], v[102:105]
	v_mfma_f32_16x16x32_bf16 v[106:109], v[90:93], v[106:109], v[142:145]
	v_mfma_f32_16x16x32_bf16 v[106:109], v[94:97], v[110:113], v[106:109]
	v_mfma_f32_16x16x32_bf16 v[110:113], v[82:85], v[114:117], v[146:149]
	v_mfma_f32_16x16x32_bf16 v[110:113], v[86:89], v[118:121], v[110:113]
	v_mfma_f32_16x16x32_bf16 v[114:117], v[90:93], v[114:117], v[138:141]
	v_mfma_f32_16x16x32_bf16 v[114:117], v[94:97], v[118:121], v[114:117]
	v_mfma_f32_16x16x32_bf16 v[118:121], v[82:85], v[122:125], v[134:137]
	v_mfma_f32_16x16x32_bf16 v[118:121], v[86:89], v[126:129], v[118:121]
	v_mfma_f32_16x16x32_bf16 v[122:125], v[90:93], v[122:125], v[130:133]
	v_mfma_f32_16x16x32_bf16 v[122:125], v[94:97], v[126:129], v[122:125]
	s_setprio 0
	s_barrier
	s_mov_b32 m0, s29
	s_mov_b32 s43, s51
	ds_read_b128 v[126:129], v244 offset:16384
	ds_read_b128 v[130:133], v244 offset:17408
	buffer_load_dwordx4 v227, s[40:43], s91 offen lds
	s_mov_b32 m0, s35
	ds_read_b128 v[134:137], v244 offset:18432
	ds_read_b128 v[138:141], v244 offset:19456
	buffer_load_dwordx4 v237, s[40:43], s91 offen lds
	s_add_i32 s93, s91, 0x1600000
	s_mov_b32 m0, s63
	ds_read_b128 v[142:145], v244 offset:20480
	ds_read_b128 v[146:149], v244 offset:21504
	buffer_load_dwordx4 v227, s[40:43], s93 offen lds
	s_mov_b32 m0, s65
	ds_read_b128 v[150:153], v244 offset:22528
	ds_read_b128 v[178:181], v244 offset:23552
	buffer_load_dwordx4 v237, s[40:43], s93 offen lds
	s_waitcnt vmcnt(6)
	s_waitcnt lgkmcnt(0)
	s_barrier
	s_setprio 1
	s_waitcnt lgkmcnt(0)
	v_mfma_f32_16x16x32_bf16 v[62:65], v[66:69], v[126:129], v[62:65]
	v_mfma_f32_16x16x32_bf16 v[62:65], v[70:73], v[130:133], v[62:65]
	v_mfma_f32_16x16x32_bf16 v[46:49], v[66:69], v[134:137], v[46:49]
	v_mfma_f32_16x16x32_bf16 v[46:49], v[70:73], v[138:141], v[46:49]
	v_mfma_f32_16x16x32_bf16 v[42:45], v[66:69], v[142:145], v[42:45]
	v_mfma_f32_16x16x32_bf16 v[42:45], v[70:73], v[146:149], v[42:45]
	v_mfma_f32_16x16x32_bf16 v[30:33], v[66:69], v[150:153], v[30:33]
	v_mfma_f32_16x16x32_bf16 v[30:33], v[70:73], v[178:181], v[30:33]
	v_mfma_f32_16x16x32_bf16 v[58:61], v[74:77], v[126:129], v[58:61]
	v_mfma_f32_16x16x32_bf16 v[58:61], v[78:81], v[130:133], v[58:61]
	v_mfma_f32_16x16x32_bf16 v[38:41], v[74:77], v[134:137], v[38:41]
	v_mfma_f32_16x16x32_bf16 v[38:41], v[78:81], v[138:141], v[38:41]
	v_mfma_f32_16x16x32_bf16 v[34:37], v[74:77], v[142:145], v[34:37]
	v_mfma_f32_16x16x32_bf16 v[34:37], v[78:81], v[146:149], v[34:37]
	v_mfma_f32_16x16x32_bf16 v[26:29], v[74:77], v[150:153], v[26:29]
	v_mfma_f32_16x16x32_bf16 v[26:29], v[78:81], v[178:181], v[26:29]
	s_setprio 0
	s_setprio 1
	v_mfma_f32_16x16x32_bf16 v[54:57], v[82:85], v[126:129], v[54:57]
	v_mfma_f32_16x16x32_bf16 v[54:57], v[86:89], v[130:133], v[54:57]
	v_mfma_f32_16x16x32_bf16 v[22:25], v[82:85], v[134:137], v[22:25]
	v_mfma_f32_16x16x32_bf16 v[22:25], v[86:89], v[138:141], v[22:25]
	v_mfma_f32_16x16x32_bf16 v[18:21], v[82:85], v[142:145], v[18:21]
	v_mfma_f32_16x16x32_bf16 v[18:21], v[86:89], v[146:149], v[18:21]
	v_mfma_f32_16x16x32_bf16 v[6:9], v[82:85], v[150:153], v[6:9]
	v_mfma_f32_16x16x32_bf16 v[6:9], v[86:89], v[178:181], v[6:9]
	v_mfma_f32_16x16x32_bf16 v[50:53], v[90:93], v[126:129], v[50:53]
	v_mfma_f32_16x16x32_bf16 v[50:53], v[94:97], v[130:133], v[50:53]
	v_mfma_f32_16x16x32_bf16 v[14:17], v[90:93], v[134:137], v[14:17]
	v_mfma_f32_16x16x32_bf16 v[14:17], v[94:97], v[138:141], v[14:17]
	v_mfma_f32_16x16x32_bf16 v[10:13], v[90:93], v[142:145], v[10:13]
	v_mfma_f32_16x16x32_bf16 v[10:13], v[94:97], v[146:149], v[10:13]
	v_mfma_f32_16x16x32_bf16 v[2:5], v[90:93], v[150:153], v[2:5]
	v_mfma_f32_16x16x32_bf16 v[2:5], v[94:97], v[178:181], v[2:5]
	s_setprio 0
	s_barrier
	ds_read_b128 v[66:69], v245
	ds_read_b128 v[70:73], v245 offset:1024
	ds_read_b128 v[74:77], v245 offset:2048
	ds_read_b128 v[78:81], v245 offset:3072
	ds_read_b128 v[82:85], v246
	ds_read_b128 v[86:89], v246 offset:1024
	ds_read_b128 v[90:93], v246 offset:2048
	ds_read_b128 v[94:97], v246 offset:3072
	s_mov_b32 m0, s3
	ds_read_b128 v[126:129], v244 offset:32768
	ds_read_b128 v[130:133], v244 offset:33792
	buffer_load_dwordx4 v1, s[48:51], s92 offen lds
	s_mov_b32 m0, s70
	ds_read_b128 v[134:137], v244 offset:34816
	ds_read_b128 v[138:141], v244 offset:35840
	buffer_load_dwordx4 v236, s[48:51], s92 offen lds
	s_add_i32 s92, s92, 0x80000
	s_mov_b32 m0, s71
	ds_read_b128 v[194:197], v244 offset:36864
	ds_read_b128 v[198:201], v244 offset:37888
	buffer_load_dwordx4 v1, s[48:51], s92 offen lds
	s_mov_b32 m0, s72
	ds_read_b128 v[202:205], v244 offset:38912
	ds_read_b128 v[206:209], v244 offset:39936
	buffer_load_dwordx4 v236, s[48:51], s92 offen lds
	s_waitcnt vmcnt(8)
	s_waitcnt lgkmcnt(0)
	s_barrier
	s_setprio 1
	s_waitcnt lgkmcnt(0)
	v_mfma_f32_16x16x32_bf16 v[142:145], v[66:69], v[126:129], v[190:193]
	v_mfma_f32_16x16x32_bf16 v[190:193], v[70:73], v[130:133], v[142:145]
	v_mfma_f32_16x16x32_bf16 v[142:145], v[74:77], v[126:129], v[186:189]
	v_mfma_f32_16x16x32_bf16 v[186:189], v[78:81], v[130:133], v[142:145]
	v_mfma_f32_16x16x32_bf16 v[142:145], v[66:69], v[134:137], v[174:177]
	v_mfma_f32_16x16x32_bf16 v[174:177], v[70:73], v[138:141], v[142:145]
	v_mfma_f32_16x16x32_bf16 v[142:145], v[74:77], v[134:137], v[166:169]
	v_mfma_f32_16x16x32_bf16 v[166:169], v[78:81], v[138:141], v[142:145]
	v_mfma_f32_16x16x32_bf16 v[142:145], v[66:69], v[194:197], v[170:173]
	v_mfma_f32_16x16x32_bf16 v[170:173], v[70:73], v[198:201], v[142:145]
	v_mfma_f32_16x16x32_bf16 v[142:145], v[74:77], v[194:197], v[162:165]
	v_mfma_f32_16x16x32_bf16 v[162:165], v[78:81], v[198:201], v[142:145]
	v_mfma_f32_16x16x32_bf16 v[142:145], v[66:69], v[202:205], v[158:161]
	v_mfma_f32_16x16x32_bf16 v[158:161], v[70:73], v[206:209], v[142:145]
	v_mfma_f32_16x16x32_bf16 v[142:145], v[74:77], v[202:205], v[154:157]
	v_mfma_f32_16x16x32_bf16 v[154:157], v[78:81], v[206:209], v[142:145]
	s_setprio 0
	s_setprio 1
	v_mfma_f32_16x16x32_bf16 v[98:101], v[90:93], v[126:129], v[98:101]
	v_mfma_f32_16x16x32_bf16 v[178:181], v[94:97], v[130:133], v[98:101]
	v_mfma_f32_16x16x32_bf16 v[98:101], v[82:85], v[134:137], v[102:105]
	v_mfma_f32_16x16x32_bf16 v[150:153], v[86:89], v[138:141], v[98:101]
	v_mfma_f32_16x16x32_bf16 v[98:101], v[90:93], v[134:137], v[106:109]
	v_mfma_f32_16x16x32_bf16 v[142:145], v[82:85], v[126:129], v[182:185]
	v_mfma_f32_16x16x32_bf16 v[182:185], v[86:89], v[130:133], v[142:145]
	v_mfma_f32_16x16x32_bf16 v[142:145], v[94:97], v[138:141], v[98:101]
	v_mfma_f32_16x16x32_bf16 v[98:101], v[82:85], v[194:197], v[110:113]
	v_mfma_f32_16x16x32_bf16 v[146:149], v[86:89], v[198:201], v[98:101]
	v_mfma_f32_16x16x32_bf16 v[98:101], v[90:93], v[194:197], v[114:117]
	v_mfma_f32_16x16x32_bf16 v[138:141], v[94:97], v[198:201], v[98:101]
	v_mfma_f32_16x16x32_bf16 v[98:101], v[82:85], v[202:205], v[118:121]
	v_mfma_f32_16x16x32_bf16 v[134:137], v[86:89], v[206:209], v[98:101]
	v_mfma_f32_16x16x32_bf16 v[98:101], v[90:93], v[202:205], v[122:125]
	v_mfma_f32_16x16x32_bf16 v[130:133], v[94:97], v[206:209], v[98:101]
	s_setprio 0
	s_barrier
	s_mov_b32 m0, s74
	s_or_b32 s92, s91, 0x80
	s_nop 2
	ds_read_b128 v[98:101], v244 offset:49152
	ds_read_b128 v[102:105], v244 offset:50176
	buffer_load_dwordx4 v227, s[40:43], s92 offen lds
	s_mov_b32 m0, s75
	ds_read_b128 v[106:109], v244 offset:51200
	ds_read_b128 v[110:113], v244 offset:52224
	buffer_load_dwordx4 v237, s[40:43], s92 offen lds
	s_add_i32 s91, s91, 0x1600080
	s_mov_b32 m0, s77
	ds_read_b128 v[114:117], v244 offset:53248
	ds_read_b128 v[118:121], v244 offset:54272
	buffer_load_dwordx4 v227, s[40:43], s91 offen lds
	s_mov_b32 m0, s78
	ds_read_b128 v[122:125], v244 offset:55296
	ds_read_b128 v[126:129], v244 offset:56320
	buffer_load_dwordx4 v237, s[40:43], s91 offen lds
	s_waitcnt vmcnt(6)
	s_waitcnt lgkmcnt(0)
	s_barrier
	s_setprio 1
	s_waitcnt lgkmcnt(0)
	v_mfma_f32_16x16x32_bf16 v[62:65], v[66:69], v[98:101], v[62:65]
	v_mfma_f32_16x16x32_bf16 v[62:65], v[70:73], v[102:105], v[62:65]
	v_mfma_f32_16x16x32_bf16 v[46:49], v[66:69], v[106:109], v[46:49]
	v_mfma_f32_16x16x32_bf16 v[46:49], v[70:73], v[110:113], v[46:49]
	v_mfma_f32_16x16x32_bf16 v[42:45], v[66:69], v[114:117], v[42:45]
	v_mfma_f32_16x16x32_bf16 v[42:45], v[70:73], v[118:121], v[42:45]
	v_mfma_f32_16x16x32_bf16 v[30:33], v[66:69], v[122:125], v[30:33]
	v_mfma_f32_16x16x32_bf16 v[30:33], v[70:73], v[126:129], v[30:33]
	v_mfma_f32_16x16x32_bf16 v[58:61], v[74:77], v[98:101], v[58:61]
	v_mfma_f32_16x16x32_bf16 v[58:61], v[78:81], v[102:105], v[58:61]
	v_mfma_f32_16x16x32_bf16 v[38:41], v[74:77], v[106:109], v[38:41]
	v_mfma_f32_16x16x32_bf16 v[38:41], v[78:81], v[110:113], v[38:41]
	v_mfma_f32_16x16x32_bf16 v[34:37], v[74:77], v[114:117], v[34:37]
	v_mfma_f32_16x16x32_bf16 v[34:37], v[78:81], v[118:121], v[34:37]
	v_mfma_f32_16x16x32_bf16 v[26:29], v[74:77], v[122:125], v[26:29]
	v_mfma_f32_16x16x32_bf16 v[26:29], v[78:81], v[126:129], v[26:29]
	s_setprio 0
	s_setprio 1
	v_mfma_f32_16x16x32_bf16 v[54:57], v[82:85], v[98:101], v[54:57]
	v_mfma_f32_16x16x32_bf16 v[54:57], v[86:89], v[102:105], v[54:57]
	v_mfma_f32_16x16x32_bf16 v[22:25], v[82:85], v[106:109], v[22:25]
	v_mfma_f32_16x16x32_bf16 v[22:25], v[86:89], v[110:113], v[22:25]
	v_mfma_f32_16x16x32_bf16 v[18:21], v[82:85], v[114:117], v[18:21]
	v_mfma_f32_16x16x32_bf16 v[18:21], v[86:89], v[118:121], v[18:21]
	v_mfma_f32_16x16x32_bf16 v[6:9], v[82:85], v[122:125], v[6:9]
	v_mfma_f32_16x16x32_bf16 v[6:9], v[86:89], v[126:129], v[6:9]
	v_mfma_f32_16x16x32_bf16 v[50:53], v[90:93], v[98:101], v[50:53]
	v_mfma_f32_16x16x32_bf16 v[50:53], v[94:97], v[102:105], v[50:53]
	v_mfma_f32_16x16x32_bf16 v[14:17], v[90:93], v[106:109], v[14:17]
	v_mfma_f32_16x16x32_bf16 v[14:17], v[94:97], v[110:113], v[14:17]
	v_mfma_f32_16x16x32_bf16 v[10:13], v[90:93], v[114:117], v[10:13]
	v_mfma_f32_16x16x32_bf16 v[10:13], v[94:97], v[118:121], v[10:13]
	v_mfma_f32_16x16x32_bf16 v[2:5], v[90:93], v[122:125], v[2:5]
	v_mfma_f32_16x16x32_bf16 v[2:5], v[94:97], v[126:129], v[2:5]
	s_setprio 0
	s_barrier
	s_add_i32 s69, s69, 2
	s_addk_i32 s67, 0x100
	s_addk_i32 s68, 0x100
	s_cmp_gt_u32 s69, 29
	s_cbranch_scc0 .LBB0_822
	s_and_b64 vcc, exec, s[38:39]
	s_cbranch_vccz .LBB0_825
	s_barrier

.LBB0_1003:
	v_add_u32_e32 v130, 0x10000, v155
	ds_read_b128 v[132:135], v130
	ds_read_b128 v[144:147], v130 offset:1024
	ds_read_b128 v[158:161], v130 offset:2048
	ds_read_b128 v[162:165], v130 offset:3072
	v_add_u32_e32 v130, 0x14000, v155
	s_lshl_b32 s39, s92, 7
	ds_read_b128 v[166:169], v130
	ds_read_b128 v[170:173], v130 offset:1024
	ds_read_b128 v[174:177], v130 offset:2048
	ds_read_b128 v[178:181], v130 offset:3072
	s_add_i32 s93, s61, s39
	s_addk_i32 s39, 0x100
	s_add_i32 s94, s93, 0x80
	s_add_i32 s95, s39, s61
	s_and_b64 s[50:51], s[48:49], exec
	s_cselect_b32 s50, s87, s95
	s_add_i32 s39, s39, s63
	s_and_b64 s[48:49], s[48:49], exec
	s_cselect_b32 s48, s88, s39
	s_or_b32 s49, s48, 0x80
	s_mov_b32 m0, s77
	ds_read_b128 v[182:185], v156
	ds_read_b128 v[186:189], v156 offset:1024
	buffer_load_dwordx4 v151, s[28:31], s94 offen lds
	s_mov_b32 m0, s78
	ds_read_b128 v[190:193], v156 offset:2048
	ds_read_b128 v[194:197], v156 offset:3072
	buffer_load_dwordx4 v153, s[28:31], s94 offen lds
	s_add_i32 s93, s93, 0x160080
	s_mov_b32 m0, s79
	ds_read_b128 v[198:201], v156 offset:4096
	ds_read_b128 v[202:205], v156 offset:5120
	buffer_load_dwordx4 v151, s[28:31], s93 offen lds
	s_mov_b32 m0, s80
	ds_read_b128 v[206:209], v156 offset:6144
	ds_read_b128 v[210:213], v156 offset:7168
	buffer_load_dwordx4 v153, s[28:31], s93 offen lds
	s_waitcnt vmcnt(8)
	s_waitcnt lgkmcnt(0)
	s_barrier
	s_setprio 1
	s_waitcnt lgkmcnt(0)
	v_mfma_f32_16x16x32_bf16 v[126:129], v[132:135], v[182:185], v[126:129]
	v_mfma_f32_16x16x32_bf16 v[126:129], v[144:147], v[186:189], v[126:129]
	v_mfma_f32_16x16x32_bf16 v[110:113], v[132:135], v[190:193], v[110:113]
	v_mfma_f32_16x16x32_bf16 v[110:113], v[144:147], v[194:197], v[110:113]
	v_mfma_f32_16x16x32_bf16 v[94:97], v[132:135], v[198:201], v[94:97]
	v_mfma_f32_16x16x32_bf16 v[94:97], v[144:147], v[202:205], v[94:97]
	v_mfma_f32_16x16x32_bf16 v[78:81], v[132:135], v[206:209], v[78:81]
	v_mfma_f32_16x16x32_bf16 v[78:81], v[144:147], v[210:213], v[78:81]
	v_mfma_f32_16x16x32_bf16 v[122:125], v[158:161], v[182:185], v[122:125]
	v_mfma_f32_16x16x32_bf16 v[122:125], v[162:165], v[186:189], v[122:125]
	v_mfma_f32_16x16x32_bf16 v[106:109], v[158:161], v[190:193], v[106:109]
	v_mfma_f32_16x16x32_bf16 v[106:109], v[162:165], v[194:197], v[106:109]
	v_mfma_f32_16x16x32_bf16 v[90:93], v[158:161], v[198:201], v[90:93]
	v_mfma_f32_16x16x32_bf16 v[90:93], v[162:165], v[202:205], v[90:93]
	v_mfma_f32_16x16x32_bf16 v[74:77], v[158:161], v[206:209], v[74:77]
	v_mfma_f32_16x16x32_bf16 v[74:77], v[162:165], v[210:213], v[74:77]
	s_setprio 0
	s_setprio 1
	v_mfma_f32_16x16x32_bf16 v[118:121], v[166:169], v[182:185], v[118:121]
	v_mfma_f32_16x16x32_bf16 v[118:121], v[170:173], v[186:189], v[118:121]
	v_mfma_f32_16x16x32_bf16 v[102:105], v[166:169], v[190:193], v[102:105]
	v_mfma_f32_16x16x32_bf16 v[102:105], v[170:173], v[194:197], v[102:105]
	v_mfma_f32_16x16x32_bf16 v[86:89], v[166:169], v[198:201], v[86:89]
	v_mfma_f32_16x16x32_bf16 v[86:89], v[170:173], v[202:205], v[86:89]
	v_mfma_f32_16x16x32_bf16 v[70:73], v[166:169], v[206:209], v[70:73]
	v_mfma_f32_16x16x32_bf16 v[70:73], v[170:173], v[210:213], v[70:73]
	v_mfma_f32_16x16x32_bf16 v[114:117], v[174:177], v[182:185], v[114:117]
	v_mfma_f32_16x16x32_bf16 v[114:117], v[178:181], v[186:189], v[114:117]
	v_mfma_f32_16x16x32_bf16 v[98:101], v[174:177], v[190:193], v[98:101]
	v_mfma_f32_16x16x32_bf16 v[98:101], v[178:181], v[194:197], v[98:101]
	v_mfma_f32_16x16x32_bf16 v[82:85], v[174:177], v[198:201], v[82:85]
	v_mfma_f32_16x16x32_bf16 v[82:85], v[178:181], v[202:205], v[82:85]
	v_mfma_f32_16x16x32_bf16 v[66:69], v[174:177], v[206:209], v[66:69]
	v_mfma_f32_16x16x32_bf16 v[66:69], v[178:181], v[210:213], v[66:69]
	s_setprio 0
	s_barrier
	s_mov_b32 m0, s64
	s_mov_b32 s39, s31
	ds_read_b128 v[182:185], v156 offset:16384
	ds_read_b128 v[186:189], v156 offset:17408
	buffer_load_dwordx4 v152, s[36:39], s48 offen lds
	s_mov_b32 m0, s65
	ds_read_b128 v[190:193], v156 offset:18432
	ds_read_b128 v[194:197], v156 offset:19456
	buffer_load_dwordx4 v154, s[36:39], s48 offen lds
	s_add_i32 s51, s48, 0x160000
	s_mov_b32 m0, s66
	ds_read_b128 v[198:201], v156 offset:20480
	ds_read_b128 v[202:205], v156 offset:21504
	buffer_load_dwordx4 v152, s[36:39], s51 offen lds
	s_mov_b32 m0, s67
	ds_read_b128 v[206:209], v156 offset:22528
	ds_read_b128 v[210:213], v156 offset:23552
	buffer_load_dwordx4 v154, s[36:39], s51 offen lds
	s_waitcnt vmcnt(6)
	s_waitcnt lgkmcnt(0)
	s_barrier
	s_setprio 1
	s_waitcnt lgkmcnt(0)
	v_mfma_f32_16x16x32_bf16 v[62:65], v[132:135], v[182:185], v[62:65]
	v_mfma_f32_16x16x32_bf16 v[62:65], v[144:147], v[186:189], v[62:65]
	v_mfma_f32_16x16x32_bf16 v[46:49], v[132:135], v[190:193], v[46:49]
	v_mfma_f32_16x16x32_bf16 v[46:49], v[144:147], v[194:197], v[46:49]
	v_mfma_f32_16x16x32_bf16 v[30:33], v[132:135], v[198:201], v[30:33]
	v_mfma_f32_16x16x32_bf16 v[30:33], v[144:147], v[202:205], v[30:33]
	v_mfma_f32_16x16x32_bf16 v[14:17], v[132:135], v[206:209], v[14:17]
	v_mfma_f32_16x16x32_bf16 v[14:17], v[144:147], v[210:213], v[14:17]
	v_mfma_f32_16x16x32_bf16 v[58:61], v[158:161], v[182:185], v[58:61]
	v_mfma_f32_16x16x32_bf16 v[58:61], v[162:165], v[186:189], v[58:61]
	v_mfma_f32_16x16x32_bf16 v[42:45], v[158:161], v[190:193], v[42:45]
	v_mfma_f32_16x16x32_bf16 v[42:45], v[162:165], v[194:197], v[42:45]
	v_mfma_f32_16x16x32_bf16 v[26:29], v[158:161], v[198:201], v[26:29]
	v_mfma_f32_16x16x32_bf16 v[26:29], v[162:165], v[202:205], v[26:29]
	v_mfma_f32_16x16x32_bf16 v[10:13], v[158:161], v[206:209], v[10:13]
	v_mfma_f32_16x16x32_bf16 v[10:13], v[162:165], v[210:213], v[10:13]
	s_setprio 0
	s_setprio 1
	v_mfma_f32_16x16x32_bf16 v[54:57], v[166:169], v[182:185], v[54:57]
	v_mfma_f32_16x16x32_bf16 v[54:57], v[170:173], v[186:189], v[54:57]
	v_mfma_f32_16x16x32_bf16 v[38:41], v[166:169], v[190:193], v[38:41]
	v_mfma_f32_16x16x32_bf16 v[38:41], v[170:173], v[194:197], v[38:41]
	v_mfma_f32_16x16x32_bf16 v[22:25], v[166:169], v[198:201], v[22:25]
	v_mfma_f32_16x16x32_bf16 v[22:25], v[170:173], v[202:205], v[22:25]
	v_mfma_f32_16x16x32_bf16 v[6:9], v[166:169], v[206:209], v[6:9]
	v_mfma_f32_16x16x32_bf16 v[6:9], v[170:173], v[210:213], v[6:9]
	v_mfma_f32_16x16x32_bf16 v[50:53], v[174:177], v[182:185], v[50:53]
	v_mfma_f32_16x16x32_bf16 v[50:53], v[178:181], v[186:189], v[50:53]
	v_mfma_f32_16x16x32_bf16 v[34:37], v[174:177], v[190:193], v[34:37]
	v_mfma_f32_16x16x32_bf16 v[34:37], v[178:181], v[194:197], v[34:37]
	v_mfma_f32_16x16x32_bf16 v[18:21], v[174:177], v[198:201], v[18:21]
	v_mfma_f32_16x16x32_bf16 v[18:21], v[178:181], v[202:205], v[18:21]
	v_mfma_f32_16x16x32_bf16 v[2:5], v[174:177], v[206:209], v[2:5]
	v_mfma_f32_16x16x32_bf16 v[2:5], v[178:181], v[210:213], v[2:5]
	s_setprio 0
	s_barrier
	v_add_u32_e32 v130, 0x18000, v155
	ds_read_b128 v[132:135], v130
	ds_read_b128 v[144:147], v130 offset:1024
	ds_read_b128 v[158:161], v130 offset:2048
	ds_read_b128 v[162:165], v130 offset:3072
	v_add_u32_e32 v130, 0x1c000, v155
	ds_read_b128 v[166:169], v130
	ds_read_b128 v[170:173], v130 offset:1024
	ds_read_b128 v[174:177], v130 offset:2048
	ds_read_b128 v[178:181], v130 offset:3072
	s_mov_b32 m0, s62
	ds_read_b128 v[182:185], v156 offset:32768
	ds_read_b128 v[186:189], v156 offset:33792
	buffer_load_dwordx4 v151, s[28:31], s50 offen lds
	s_mov_b32 m0, s68
	ds_read_b128 v[190:193], v156 offset:34816
	ds_read_b128 v[194:197], v156 offset:35840
	buffer_load_dwordx4 v153, s[28:31], s50 offen lds
	s_add_i32 s50, s50, 0x160000
	s_mov_b32 m0, s69
	ds_read_b128 v[198:201], v156 offset:36864
	ds_read_b128 v[202:205], v156 offset:37888
	buffer_load_dwordx4 v151, s[28:31], s50 offen lds
	s_mov_b32 m0, s70
	ds_read_b128 v[206:209], v156 offset:38912
	ds_read_b128 v[210:213], v156 offset:39936
	buffer_load_dwordx4 v153, s[28:31], s50 offen lds
	s_waitcnt vmcnt(8)
	s_waitcnt lgkmcnt(0)
	s_barrier
	s_setprio 1
	s_waitcnt lgkmcnt(0)
	v_mfma_f32_16x16x32_bf16 v[126:129], v[132:135], v[182:185], v[126:129]
	v_mfma_f32_16x16x32_bf16 v[126:129], v[144:147], v[186:189], v[126:129]
	v_mfma_f32_16x16x32_bf16 v[110:113], v[132:135], v[190:193], v[110:113]
	v_mfma_f32_16x16x32_bf16 v[110:113], v[144:147], v[194:197], v[110:113]
	v_mfma_f32_16x16x32_bf16 v[94:97], v[132:135], v[198:201], v[94:97]
	v_mfma_f32_16x16x32_bf16 v[94:97], v[144:147], v[202:205], v[94:97]
	v_mfma_f32_16x16x32_bf16 v[78:81], v[132:135], v[206:209], v[78:81]
	v_mfma_f32_16x16x32_bf16 v[78:81], v[144:147], v[210:213], v[78:81]
	v_mfma_f32_16x16x32_bf16 v[122:125], v[158:161], v[182:185], v[122:125]
	v_mfma_f32_16x16x32_bf16 v[122:125], v[162:165], v[186:189], v[122:125]
	v_mfma_f32_16x16x32_bf16 v[106:109], v[158:161], v[190:193], v[106:109]
	v_mfma_f32_16x16x32_bf16 v[106:109], v[162:165], v[194:197], v[106:109]
	v_mfma_f32_16x16x32_bf16 v[90:93], v[158:161], v[198:201], v[90:93]
	v_mfma_f32_16x16x32_bf16 v[90:93], v[162:165], v[202:205], v[90:93]
	v_mfma_f32_16x16x32_bf16 v[74:77], v[158:161], v[206:209], v[74:77]
	v_mfma_f32_16x16x32_bf16 v[74:77], v[162:165], v[210:213], v[74:77]
	s_setprio 0
	s_setprio 1
	v_mfma_f32_16x16x32_bf16 v[118:121], v[166:169], v[182:185], v[118:121]
	v_mfma_f32_16x16x32_bf16 v[118:121], v[170:173], v[186:189], v[118:121]
	v_mfma_f32_16x16x32_bf16 v[102:105], v[166:169], v[190:193], v[102:105]
	v_mfma_f32_16x16x32_bf16 v[102:105], v[170:173], v[194:197], v[102:105]
	v_mfma_f32_16x16x32_bf16 v[86:89], v[166:169], v[198:201], v[86:89]
	v_mfma_f32_16x16x32_bf16 v[86:89], v[170:173], v[202:205], v[86:89]
	v_mfma_f32_16x16x32_bf16 v[70:73], v[166:169], v[206:209], v[70:73]
	v_mfma_f32_16x16x32_bf16 v[70:73], v[170:173], v[210:213], v[70:73]
	v_mfma_f32_16x16x32_bf16 v[114:117], v[174:177], v[182:185], v[114:117]
	v_mfma_f32_16x16x32_bf16 v[114:117], v[178:181], v[186:189], v[114:117]
	v_mfma_f32_16x16x32_bf16 v[98:101], v[174:177], v[190:193], v[98:101]
	v_mfma_f32_16x16x32_bf16 v[98:101], v[178:181], v[194:197], v[98:101]
	v_mfma_f32_16x16x32_bf16 v[82:85], v[174:177], v[198:201], v[82:85]
	v_mfma_f32_16x16x32_bf16 v[82:85], v[178:181], v[202:205], v[82:85]
	v_mfma_f32_16x16x32_bf16 v[66:69], v[174:177], v[206:209], v[66:69]
	v_mfma_f32_16x16x32_bf16 v[66:69], v[178:181], v[210:213], v[66:69]
	s_setprio 0
	s_barrier
	s_mov_b32 m0, s72
	ds_read_b128 v[182:185], v156 offset:49152
	ds_read_b128 v[186:189], v156 offset:50176
	buffer_load_dwordx4 v152, s[36:39], s49 offen lds
	s_mov_b32 m0, s73
	ds_read_b128 v[190:193], v156 offset:51200
	ds_read_b128 v[194:197], v156 offset:52224
	buffer_load_dwordx4 v154, s[36:39], s49 offen lds
	s_add_i32 s48, s48, 0x160080
	s_mov_b32 m0, s74
	ds_read_b128 v[198:201], v156 offset:53248
	ds_read_b128 v[202:205], v156 offset:54272
	buffer_load_dwordx4 v152, s[36:39], s48 offen lds
	s_mov_b32 m0, s75
	ds_read_b128 v[206:209], v156 offset:55296
	ds_read_b128 v[210:213], v156 offset:56320
	buffer_load_dwordx4 v154, s[36:39], s48 offen lds
	s_waitcnt vmcnt(6)
	s_waitcnt lgkmcnt(0)
	s_barrier
	s_setprio 1
	s_waitcnt lgkmcnt(0)
	v_mfma_f32_16x16x32_bf16 v[62:65], v[132:135], v[182:185], v[62:65]
	v_mfma_f32_16x16x32_bf16 v[62:65], v[144:147], v[186:189], v[62:65]
	v_mfma_f32_16x16x32_bf16 v[46:49], v[132:135], v[190:193], v[46:49]
	v_mfma_f32_16x16x32_bf16 v[46:49], v[144:147], v[194:197], v[46:49]
	v_mfma_f32_16x16x32_bf16 v[30:33], v[132:135], v[198:201], v[30:33]
	v_mfma_f32_16x16x32_bf16 v[30:33], v[144:147], v[202:205], v[30:33]
	v_mfma_f32_16x16x32_bf16 v[14:17], v[132:135], v[206:209], v[14:17]
	v_mfma_f32_16x16x32_bf16 v[14:17], v[144:147], v[210:213], v[14:17]
	v_mfma_f32_16x16x32_bf16 v[58:61], v[158:161], v[182:185], v[58:61]
	v_mfma_f32_16x16x32_bf16 v[58:61], v[162:165], v[186:189], v[58:61]
	v_mfma_f32_16x16x32_bf16 v[42:45], v[158:161], v[190:193], v[42:45]
	v_mfma_f32_16x16x32_bf16 v[42:45], v[162:165], v[194:197], v[42:45]
	v_mfma_f32_16x16x32_bf16 v[26:29], v[158:161], v[198:201], v[26:29]
	v_mfma_f32_16x16x32_bf16 v[26:29], v[162:165], v[202:205], v[26:29]
	v_mfma_f32_16x16x32_bf16 v[10:13], v[158:161], v[206:209], v[10:13]
	v_mfma_f32_16x16x32_bf16 v[10:13], v[162:165], v[210:213], v[10:13]
	s_setprio 0
	s_setprio 1
	v_mfma_f32_16x16x32_bf16 v[54:57], v[166:169], v[182:185], v[54:57]
	v_mfma_f32_16x16x32_bf16 v[54:57], v[170:173], v[186:189], v[54:57]
	v_mfma_f32_16x16x32_bf16 v[38:41], v[166:169], v[190:193], v[38:41]
	v_mfma_f32_16x16x32_bf16 v[38:41], v[170:173], v[194:197], v[38:41]
	v_mfma_f32_16x16x32_bf16 v[22:25], v[166:169], v[198:201], v[22:25]
	v_mfma_f32_16x16x32_bf16 v[22:25], v[170:173], v[202:205], v[22:25]
	v_mfma_f32_16x16x32_bf16 v[6:9], v[166:169], v[206:209], v[6:9]
	v_mfma_f32_16x16x32_bf16 v[6:9], v[170:173], v[210:213], v[6:9]
	v_mfma_f32_16x16x32_bf16 v[50:53], v[174:177], v[182:185], v[50:53]
	v_mfma_f32_16x16x32_bf16 v[50:53], v[178:181], v[186:189], v[50:53]
	v_mfma_f32_16x16x32_bf16 v[34:37], v[174:177], v[190:193], v[34:37]
	v_mfma_f32_16x16x32_bf16 v[34:37], v[178:181], v[194:197], v[34:37]
	v_mfma_f32_16x16x32_bf16 v[18:21], v[174:177], v[198:201], v[18:21]
	v_mfma_f32_16x16x32_bf16 v[18:21], v[178:181], v[202:205], v[18:21]
	v_mfma_f32_16x16x32_bf16 v[2:5], v[174:177], v[206:209], v[2:5]
	v_mfma_f32_16x16x32_bf16 v[2:5], v[178:181], v[210:213], v[2:5]
	s_setprio 0
	s_barrier
	s_add_i32 s39, s92, 2
	s_cmpk_gt_u32 s92, 0x55
	s_cbranch_scc1 .LBB0_1005
	s_mov_b32 s92, s39
	s_branch .LBB0_999
